# gate-GEMM and out-projection epilogues hand-written with prefetched row data and counted waits; plus attention stagger and earlier edits
# speedup vs baseline: 1.0156x; 1.0156x over previous
; __device__ __forceinline__ unsigned cvt_pk_bf16(float lo, float hi) { unsigned r; asm volatile("v_cvt_pk_bf16_f32 %0, %1, %2" : "=v"(r) : "v"(lo), "v"(hi)); return r; }
; __device__ __forceinline__ float bf_lo(unsigned w) { return __uint_as_float(w << 16); }
; __device__ __forceinline__ float bf_hi(unsigned w) { return __uint_as_float(w & 0xffff0000u); }
;     __device__ __forceinline__ void operator()(const f32x4 (&acc)[2][2][4][2], const Unit& u, int wr, int wc, int fr, int fq) const {
;     ...
;         for (int bj = 0; bj < 2; ++bj) { const int col = col0 + bj * HALF;
;             f32x4 c1[2], c2[2], lg[2], lb[2];
; #pragma unroll
;             for (int n = 0; n < 2; ++n) { c1[n] = *(const f32x4*)(C1 + col + 4 * n); c2[n] = *(const f32x4*)(C2 + col + 4 * n); lg[n] = *(const f32x4*)(LG + col + 4 * n); lb[n] = *(const f32x4*)(LB + col + 4 * n); }
; #pragma unroll
;             for (int ai = 0; ai < 2; ++ai)
; #pragma unroll
;                 for (int m = 0; m < 4; ++m) { const int row = row0 + ai * HALF + m * 16; const size_t o2 = (size_t)row * ldc + col;
;                     const float s1 = ST[2 * row], s2 = ST[2 * row + 1], mu = s1 * (1.f / 2048.f), rstd = __builtin_amdgcn_rsqf(fmaxf(s2 * (1.f / 2048.f) - mu * mu, 0.f) + 1e-5f);
;                     const u32x4 zw = *(const u32x4*)(Zb + o2), pw = *(const u32x4*)(PE + o2); u32x4 xw;
; #pragma unroll
;                     for (int n = 0; n < 2; ++n) { const unsigned za = n ? zw.z : zw.x, zb2 = n ? zw.w : zw.y, pa = n ? pw.z : pw.x, pb = n ? pw.w : pw.y;
;                         const float zv[4] = {bf_lo(za), bf_hi(za), bf_lo(zb2), bf_hi(zb2)}, pv[4] = {bf_lo(pa), bf_hi(pa), bf_lo(pb), bf_hi(pb)}; const f32x4 a = acc[ai][bj][m][n]; f32x4 o;
; #pragma unroll
;                         for (int e = 0; e < 4; ++e) { const float sv = rstd * (a[e] - mu * c1[n][e]) + c2[n][e]; const float xl = (zv[e] - mu) * rstd * lg[n][e] + lb[n][e]; o[e] = xl + pv[e] * __builtin_amdgcn_rcpf(1.f + __expf(-sv)); }
;                         *(f32x4*)(OUTF + o2 + 4 * n) = o; if (n == 0) { xw.x = cvt_pk_bf16(o[0], o[1]); xw.y = cvt_pk_bf16(o[2], o[3]); } else { xw.z = cvt_pk_bf16(o[0], o[1]); xw.w = cvt_pk_bf16(o[2], o[3]); } }
;                     if (XB) *(u32x4*)(XB + o2) = xw; }
.LBB0_1344:
	v_lshl_add_u32 v226, s41, 8, v205
	v_lshl_or_b32 v224, s40, 8, v207
	v_lshlrev_b32_e32 v209, 3, v226
	v_lshlrev_b32_e32 v225, 2, v224
	v_lshlrev_b32_e32 v224, 1, v224
	v_lshl_add_u32 v204, v226, 12, v224
	v_readlane_b32 s2, v255, 48
	v_readlane_b32 s3, v255, 49
	s_mov_b32 s0, 0x3a000000
	s_mov_b64 s[74:75], 0x80000
	global_load_dwordx4 v[88:91], v225, s[96:97]
	global_load_dwordx4 v[96:99], v225, s[4:5]
	global_load_dwordx4 v[104:107], v225, s[56:57]
	global_load_dwordx4 v[116:119], v225, s[58:59]
	global_load_dwordx4 v[92:95], v225, s[96:97] offset:16
	global_load_dwordx4 v[100:103], v225, s[4:5] offset:16
	global_load_dwordx4 v[108:111], v225, s[56:57] offset:16
	global_load_dwordx4 v[124:127], v225, s[58:59] offset:16
	global_load_dwordx2 v[160:161], v209, s[94:95]
	global_load_dwordx4 v[164:167], v204, s[82:83]
	global_load_dwordx4 v[184:187], v204, s[92:93]
	v_mov_b32_e32 v226, v204
	v_add_u32_e32 v204, 0x10000, v204
	global_load_dwordx2 v[162:163], v209, s[94:95] offset:128
	global_load_dwordx4 v[188:191], v204, s[82:83]
	global_load_dwordx4 v[192:195], v204, s[92:93]
	s_waitcnt vmcnt(3)
	v_pk_mul_f32 v[210:211], v[160:161], s[0:1] op_sel_hi:[1,0]
	v_lshlrev_b32_e32 v224, 1, v226
	v_fma_f32 v212, -v210, v210, v211
	v_max_f32_e32 v212, 0, v212
	v_add_f32_e32 v212, 0x3727c5ac, v212
	v_rsq_f32_e32 v212, v212
	v_fma_f32 v156, -v88, v210, v156
	v_fma_f32 v157, -v89, v210, v157
	v_fma_f32 v158, -v90, v210, v158
	v_fma_f32 v159, -v91, v210, v159
	v_fma_f32 v156, v156, v212, v96
	v_fma_f32 v157, v157, v212, v97
	v_fma_f32 v158, v158, v212, v98
	v_fma_f32 v159, v159, v212, v99
	v_mul_f32_e32 v156, 0xbfb8aa3b, v156
	v_mul_f32_e32 v157, 0xbfb8aa3b, v157
	v_mul_f32_e32 v158, 0xbfb8aa3b, v158
	v_mul_f32_e32 v159, 0xbfb8aa3b, v159
	v_exp_f32_e32 v156, v156
	v_exp_f32_e32 v157, v157
	v_exp_f32_e32 v158, v158
	v_exp_f32_e32 v159, v159
	v_add_f32_e32 v156, 1.0, v156
	v_add_f32_e32 v157, 1.0, v157
	v_add_f32_e32 v158, 1.0, v158
	v_add_f32_e32 v159, 1.0, v159
	v_rcp_f32_e32 v156, v156
	v_rcp_f32_e32 v157, v157
	v_rcp_f32_e32 v158, v158
	v_rcp_f32_e32 v159, v159
	v_lshlrev_b32_e32 v202, 16, v164
	v_and_b32_e32 v203, 0xffff0000, v164
	v_lshlrev_b32_e32 v200, 16, v184
	v_and_b32_e32 v201, 0xffff0000, v184
	v_pk_add_f32 v[202:203], v[202:203], v[210:211] op_sel_hi:[1,0] neg_lo:[0,1] neg_hi:[0,1]
	v_pk_mul_f32 v[202:203], v[212:213], v[202:203] op_sel_hi:[0,1]
	v_pk_fma_f32 v[202:203], v[104:105], v[202:203], v[116:117]
	v_pk_fma_f32 v[156:157], v[156:157], v[200:201], v[202:203]
	v_lshlrev_b32_e32 v202, 16, v165
	v_and_b32_e32 v203, 0xffff0000, v165
	v_lshlrev_b32_e32 v200, 16, v185
	v_and_b32_e32 v201, 0xffff0000, v185
	v_pk_add_f32 v[202:203], v[202:203], v[210:211] op_sel_hi:[1,0] neg_lo:[0,1] neg_hi:[0,1]
	v_pk_mul_f32 v[202:203], v[212:213], v[202:203] op_sel_hi:[0,1]
	v_pk_fma_f32 v[202:203], v[106:107], v[202:203], v[118:119]
	v_pk_fma_f32 v[158:159], v[158:159], v[200:201], v[202:203]
	global_store_dwordx4 v224, v[156:159], s[8:9]
	v_cvt_pk_bf16_f32 v196, v156, v157
	v_cvt_pk_bf16_f32 v197, v158, v159
	v_fma_f32 v152, -v92, v210, v152
	v_fma_f32 v153, -v93, v210, v153
	v_fma_f32 v154, -v94, v210, v154
	v_fma_f32 v155, -v95, v210, v155
	v_fma_f32 v152, v152, v212, v100
	v_fma_f32 v153, v153, v212, v101
	v_fma_f32 v154, v154, v212, v102
	v_fma_f32 v155, v155, v212, v103
	v_mul_f32_e32 v152, 0xbfb8aa3b, v152
	v_mul_f32_e32 v153, 0xbfb8aa3b, v153
	v_mul_f32_e32 v154, 0xbfb8aa3b, v154
	v_mul_f32_e32 v155, 0xbfb8aa3b, v155
	v_exp_f32_e32 v152, v152
	v_exp_f32_e32 v153, v153
	v_exp_f32_e32 v154, v154
	v_exp_f32_e32 v155, v155
	v_add_f32_e32 v152, 1.0, v152
	v_add_f32_e32 v153, 1.0, v153
	v_add_f32_e32 v154, 1.0, v154
	v_add_f32_e32 v155, 1.0, v155
	v_rcp_f32_e32 v152, v152
	v_rcp_f32_e32 v153, v153
	v_rcp_f32_e32 v154, v154
	v_rcp_f32_e32 v155, v155
	v_lshlrev_b32_e32 v202, 16, v166
	v_and_b32_e32 v203, 0xffff0000, v166
	v_lshlrev_b32_e32 v200, 16, v186
	v_and_b32_e32 v201, 0xffff0000, v186
	v_pk_add_f32 v[202:203], v[202:203], v[210:211] op_sel_hi:[1,0] neg_lo:[0,1] neg_hi:[0,1]
	v_pk_mul_f32 v[202:203], v[212:213], v[202:203] op_sel_hi:[0,1]
	v_pk_fma_f32 v[202:203], v[108:109], v[202:203], v[124:125]
	v_pk_fma_f32 v[152:153], v[152:153], v[200:201], v[202:203]
	v_lshlrev_b32_e32 v202, 16, v167
	v_and_b32_e32 v203, 0xffff0000, v167
	v_lshlrev_b32_e32 v200, 16, v187
	v_and_b32_e32 v201, 0xffff0000, v187
	v_pk_add_f32 v[202:203], v[202:203], v[210:211] op_sel_hi:[1,0] neg_lo:[0,1] neg_hi:[0,1]
	v_pk_mul_f32 v[202:203], v[212:213], v[202:203] op_sel_hi:[0,1]
	v_pk_fma_f32 v[202:203], v[110:111], v[202:203], v[126:127]
	v_pk_fma_f32 v[154:155], v[154:155], v[200:201], v[202:203]
	global_store_dwordx4 v224, v[152:155], s[8:9] offset:16
	v_cvt_pk_bf16_f32 v198, v152, v153
	v_cvt_pk_bf16_f32 v199, v154, v155
	s_and_b64 vcc, exec, s[2:3]
	s_cbranch_vccz .Lpg_nx_0
	global_store_dwordx4 v226, v[196:199], s[90:91]
; __device__ __forceinline__ unsigned cvt_pk_bf16(float lo, float hi) { unsigned r; asm volatile("v_cvt_pk_bf16_f32 %0, %1, %2" : "=v"(r) : "v"(lo), "v"(hi)); return r; }
; __device__ __forceinline__ float bf_lo(unsigned w) { return __uint_as_float(w << 16); }
; __device__ __forceinline__ float bf_hi(unsigned w) { return __uint_as_float(w & 0xffff0000u); }
;     __device__ __forceinline__ void operator()(const f32x4 (&acc)[2][2][4][2], const Unit& u, int wr, int wc, int fr, int fq) const {
;     ...
;         for (int bj = 0; bj < 2; ++bj) { const int col = col0 + bj * HALF;
;             f32x4 c1[2], c2[2], lg[2], lb[2];
; #pragma unroll
;             for (int n = 0; n < 2; ++n) { c1[n] = *(const f32x4*)(C1 + col + 4 * n); c2[n] = *(const f32x4*)(C2 + col + 4 * n); lg[n] = *(const f32x4*)(LG + col + 4 * n); lb[n] = *(const f32x4*)(LB + col + 4 * n); }
; #pragma unroll
;             for (int ai = 0; ai < 2; ++ai)
; #pragma unroll
;                 for (int m = 0; m < 4; ++m) { const int row = row0 + ai * HALF + m * 16; const size_t o2 = (size_t)row * ldc + col;
;                     const float s1 = ST[2 * row], s2 = ST[2 * row + 1], mu = s1 * (1.f / 2048.f), rstd = __builtin_amdgcn_rsqf(fmaxf(s2 * (1.f / 2048.f) - mu * mu, 0.f) + 1e-5f);
;                     const u32x4 zw = *(const u32x4*)(Zb + o2), pw = *(const u32x4*)(PE + o2); u32x4 xw;
; #pragma unroll
;                     for (int n = 0; n < 2; ++n) { const unsigned za = n ? zw.z : zw.x, zb2 = n ? zw.w : zw.y, pa = n ? pw.z : pw.x, pb = n ? pw.w : pw.y;
;                         const float zv[4] = {bf_lo(za), bf_hi(za), bf_lo(zb2), bf_hi(zb2)}, pv[4] = {bf_lo(pa), bf_hi(pa), bf_lo(pb), bf_hi(pb)}; const f32x4 a = acc[ai][bj][m][n]; f32x4 o;
; #pragma unroll
;                         for (int e = 0; e < 4; ++e) { const float sv = rstd * (a[e] - mu * c1[n][e]) + c2[n][e]; const float xl = (zv[e] - mu) * rstd * lg[n][e] + lb[n][e]; o[e] = xl + pv[e] * __builtin_amdgcn_rcpf(1.f + __expf(-sv)); }
;                         *(f32x4*)(OUTF + o2 + 4 * n) = o; if (n == 0) { xw.x = cvt_pk_bf16(o[0], o[1]); xw.y = cvt_pk_bf16(o[2], o[3]); } else { xw.z = cvt_pk_bf16(o[0], o[1]); xw.w = cvt_pk_bf16(o[2], o[3]); } }
;                     if (XB) *(u32x4*)(XB + o2) = xw; }
.Lpg_nx_0:
	v_mov_b32_e32 v226, v204
	v_add_u32_e32 v204, 0x10000, v204
	global_load_dwordx2 v[160:161], v209, s[94:95] offset:256
	global_load_dwordx4 v[164:167], v204, s[82:83]
	global_load_dwordx4 v[184:187], v204, s[92:93]
	s_and_b64 vcc, exec, s[2:3]
	s_cbranch_vccz .Lpg_w2_1
	s_waitcnt vmcnt(6)
	s_branch .Lpg_wd_1
.Lpg_w2_1:
	s_waitcnt vmcnt(5)
.Lpg_wd_1:
	v_pk_mul_f32 v[210:211], v[162:163], s[0:1] op_sel_hi:[1,0]
	v_lshlrev_b32_e32 v224, 1, v226
	v_fma_f32 v212, -v210, v210, v211
	v_max_f32_e32 v212, 0, v212
	v_add_f32_e32 v212, 0x3727c5ac, v212
	v_rsq_f32_e32 v212, v212
	v_fma_f32 v148, -v88, v210, v148
	v_fma_f32 v149, -v89, v210, v149
	v_fma_f32 v150, -v90, v210, v150
	v_fma_f32 v151, -v91, v210, v151
	v_fma_f32 v148, v148, v212, v96
	v_fma_f32 v149, v149, v212, v97
	v_fma_f32 v150, v150, v212, v98
	v_fma_f32 v151, v151, v212, v99
	v_mul_f32_e32 v148, 0xbfb8aa3b, v148
	v_mul_f32_e32 v149, 0xbfb8aa3b, v149
	v_mul_f32_e32 v150, 0xbfb8aa3b, v150
	v_mul_f32_e32 v151, 0xbfb8aa3b, v151
	v_exp_f32_e32 v148, v148
	v_exp_f32_e32 v149, v149
	v_exp_f32_e32 v150, v150
	v_exp_f32_e32 v151, v151
	v_add_f32_e32 v148, 1.0, v148
	v_add_f32_e32 v149, 1.0, v149
	v_add_f32_e32 v150, 1.0, v150
	v_add_f32_e32 v151, 1.0, v151
	v_rcp_f32_e32 v148, v148
	v_rcp_f32_e32 v149, v149
	v_rcp_f32_e32 v150, v150
	v_rcp_f32_e32 v151, v151
	v_lshlrev_b32_e32 v202, 16, v188
	v_and_b32_e32 v203, 0xffff0000, v188
	v_lshlrev_b32_e32 v200, 16, v192
	v_and_b32_e32 v201, 0xffff0000, v192
	v_pk_add_f32 v[202:203], v[202:203], v[210:211] op_sel_hi:[1,0] neg_lo:[0,1] neg_hi:[0,1]
	v_pk_mul_f32 v[202:203], v[212:213], v[202:203] op_sel_hi:[0,1]
	v_pk_fma_f32 v[202:203], v[104:105], v[202:203], v[116:117]
	v_pk_fma_f32 v[148:149], v[148:149], v[200:201], v[202:203]
	v_lshlrev_b32_e32 v202, 16, v189
	v_and_b32_e32 v203, 0xffff0000, v189
	v_lshlrev_b32_e32 v200, 16, v193
	v_and_b32_e32 v201, 0xffff0000, v193
	v_pk_add_f32 v[202:203], v[202:203], v[210:211] op_sel_hi:[1,0] neg_lo:[0,1] neg_hi:[0,1]
	v_pk_mul_f32 v[202:203], v[212:213], v[202:203] op_sel_hi:[0,1]
	v_pk_fma_f32 v[202:203], v[106:107], v[202:203], v[118:119]
	v_pk_fma_f32 v[150:151], v[150:151], v[200:201], v[202:203]
	global_store_dwordx4 v224, v[148:151], s[8:9]
	v_cvt_pk_bf16_f32 v196, v148, v149
	v_cvt_pk_bf16_f32 v197, v150, v151
	v_fma_f32 v144, -v92, v210, v144
	v_fma_f32 v145, -v93, v210, v145
	v_fma_f32 v146, -v94, v210, v146
	v_fma_f32 v147, -v95, v210, v147
	v_fma_f32 v144, v144, v212, v100
	v_fma_f32 v145, v145, v212, v101
	v_fma_f32 v146, v146, v212, v102
	v_fma_f32 v147, v147, v212, v103
	v_mul_f32_e32 v144, 0xbfb8aa3b, v144
	v_mul_f32_e32 v145, 0xbfb8aa3b, v145
	v_mul_f32_e32 v146, 0xbfb8aa3b, v146
	v_mul_f32_e32 v147, 0xbfb8aa3b, v147
	v_exp_f32_e32 v144, v144
	v_exp_f32_e32 v145, v145
	v_exp_f32_e32 v146, v146
	v_exp_f32_e32 v147, v147
	v_add_f32_e32 v144, 1.0, v144
	v_add_f32_e32 v145, 1.0, v145
	v_add_f32_e32 v146, 1.0, v146
	v_add_f32_e32 v147, 1.0, v147
	v_rcp_f32_e32 v144, v144
	v_rcp_f32_e32 v145, v145
	v_rcp_f32_e32 v146, v146
	v_rcp_f32_e32 v147, v147
	v_lshlrev_b32_e32 v202, 16, v190
	v_and_b32_e32 v203, 0xffff0000, v190
	v_lshlrev_b32_e32 v200, 16, v194
	v_and_b32_e32 v201, 0xffff0000, v194
	v_pk_add_f32 v[202:203], v[202:203], v[210:211] op_sel_hi:[1,0] neg_lo:[0,1] neg_hi:[0,1]
	v_pk_mul_f32 v[202:203], v[212:213], v[202:203] op_sel_hi:[0,1]
	v_pk_fma_f32 v[202:203], v[108:109], v[202:203], v[124:125]
	v_pk_fma_f32 v[144:145], v[144:145], v[200:201], v[202:203]
	v_lshlrev_b32_e32 v202, 16, v191
	v_and_b32_e32 v203, 0xffff0000, v191
	v_lshlrev_b32_e32 v200, 16, v195
	v_and_b32_e32 v201, 0xffff0000, v195
	v_pk_add_f32 v[202:203], v[202:203], v[210:211] op_sel_hi:[1,0] neg_lo:[0,1] neg_hi:[0,1]
	v_pk_mul_f32 v[202:203], v[212:213], v[202:203] op_sel_hi:[0,1]
	v_pk_fma_f32 v[202:203], v[110:111], v[202:203], v[126:127]
	v_pk_fma_f32 v[146:147], v[146:147], v[200:201], v[202:203]
	global_store_dwordx4 v224, v[144:147], s[8:9] offset:16
	v_cvt_pk_bf16_f32 v198, v144, v145
	v_cvt_pk_bf16_f32 v199, v146, v147
	s_and_b64 vcc, exec, s[2:3]
	s_cbranch_vccz .Lpg_nx_1
	global_store_dwordx4 v226, v[196:199], s[90:91]
.Lpg_nx_1:
	v_mov_b32_e32 v226, v204
	v_add_u32_e32 v204, 0x10000, v204
	global_load_dwordx2 v[162:163], v209, s[94:95] offset:384
	global_load_dwordx4 v[188:191], v204, s[82:83]
	global_load_dwordx4 v[192:195], v204, s[92:93]
	s_and_b64 vcc, exec, s[2:3]
	s_cbranch_vccz .Lpg_w2_2
	s_waitcnt vmcnt(6)
	s_branch .Lpg_wd_2

; __device__ __forceinline__ unsigned cvt_pk_bf16(float lo, float hi) { unsigned r; asm volatile("v_cvt_pk_bf16_f32 %0, %1, %2" : "=v"(r) : "v"(lo), "v"(hi)); return r; }
; __device__ __forceinline__ float bf_lo(unsigned w) { return __uint_as_float(w << 16); }
; __device__ __forceinline__ float bf_hi(unsigned w) { return __uint_as_float(w & 0xffff0000u); }
;     __device__ __forceinline__ void operator()(const f32x4 (&acc)[2][2][4][2], const Unit& u, int wr, int wc, int fr, int fq) const {
;     ...
;         for (int bj = 0; bj < 2; ++bj) { const int col = col0 + bj * HALF;
;             f32x4 c1[2], c2[2], lg[2], lb[2];
; #pragma unroll
;             for (int n = 0; n < 2; ++n) { c1[n] = *(const f32x4*)(C1 + col + 4 * n); c2[n] = *(const f32x4*)(C2 + col + 4 * n); lg[n] = *(const f32x4*)(LG + col + 4 * n); lb[n] = *(const f32x4*)(LB + col + 4 * n); }
; #pragma unroll
;             for (int ai = 0; ai < 2; ++ai)
; #pragma unroll
;                 for (int m = 0; m < 4; ++m) { const int row = row0 + ai * HALF + m * 16; const size_t o2 = (size_t)row * ldc + col;
;                     const float s1 = ST[2 * row], s2 = ST[2 * row + 1], mu = s1 * (1.f / 2048.f), rstd = __builtin_amdgcn_rsqf(fmaxf(s2 * (1.f / 2048.f) - mu * mu, 0.f) + 1e-5f);
;                     const u32x4 zw = *(const u32x4*)(Zb + o2), pw = *(const u32x4*)(PE + o2); u32x4 xw;
; #pragma unroll
;                     for (int n = 0; n < 2; ++n) { const unsigned za = n ? zw.z : zw.x, zb2 = n ? zw.w : zw.y, pa = n ? pw.z : pw.x, pb = n ? pw.w : pw.y;
;                         const float zv[4] = {bf_lo(za), bf_hi(za), bf_lo(zb2), bf_hi(zb2)}, pv[4] = {bf_lo(pa), bf_hi(pa), bf_lo(pb), bf_hi(pb)}; const f32x4 a = acc[ai][bj][m][n]; f32x4 o;
; #pragma unroll
;                         for (int e = 0; e < 4; ++e) { const float sv = rstd * (a[e] - mu * c1[n][e]) + c2[n][e]; const float xl = (zv[e] - mu) * rstd * lg[n][e] + lb[n][e]; o[e] = xl + pv[e] * __builtin_amdgcn_rcpf(1.f + __expf(-sv)); }
;                         *(f32x4*)(OUTF + o2 + 4 * n) = o; if (n == 0) { xw.x = cvt_pk_bf16(o[0], o[1]); xw.y = cvt_pk_bf16(o[2], o[3]); } else { xw.z = cvt_pk_bf16(o[0], o[1]); xw.w = cvt_pk_bf16(o[2], o[3]); } }
;                     if (XB) *(u32x4*)(XB + o2) = xw; }
.Lpg_wd_2:
	v_pk_mul_f32 v[210:211], v[160:161], s[0:1] op_sel_hi:[1,0]
	v_lshlrev_b32_e32 v224, 1, v226
	v_fma_f32 v212, -v210, v210, v211
	v_max_f32_e32 v212, 0, v212
	v_add_f32_e32 v212, 0x3727c5ac, v212
	v_rsq_f32_e32 v212, v212
	v_fma_f32 v140, -v88, v210, v140
	v_fma_f32 v141, -v89, v210, v141
	v_fma_f32 v142, -v90, v210, v142
	v_fma_f32 v143, -v91, v210, v143
	v_fma_f32 v140, v140, v212, v96
	v_fma_f32 v141, v141, v212, v97
	v_fma_f32 v142, v142, v212, v98
	v_fma_f32 v143, v143, v212, v99
	v_mul_f32_e32 v140, 0xbfb8aa3b, v140
	v_mul_f32_e32 v141, 0xbfb8aa3b, v141
	v_mul_f32_e32 v142, 0xbfb8aa3b, v142
	v_mul_f32_e32 v143, 0xbfb8aa3b, v143
	v_exp_f32_e32 v140, v140
	v_exp_f32_e32 v141, v141
	v_exp_f32_e32 v142, v142
	v_exp_f32_e32 v143, v143
	v_add_f32_e32 v140, 1.0, v140
	v_add_f32_e32 v141, 1.0, v141
	v_add_f32_e32 v142, 1.0, v142
	v_add_f32_e32 v143, 1.0, v143
	v_rcp_f32_e32 v140, v140
	v_rcp_f32_e32 v141, v141
	v_rcp_f32_e32 v142, v142
	v_rcp_f32_e32 v143, v143
	v_lshlrev_b32_e32 v202, 16, v164
	v_and_b32_e32 v203, 0xffff0000, v164
	v_lshlrev_b32_e32 v200, 16, v184
	v_and_b32_e32 v201, 0xffff0000, v184
	v_pk_add_f32 v[202:203], v[202:203], v[210:211] op_sel_hi:[1,0] neg_lo:[0,1] neg_hi:[0,1]
	v_pk_mul_f32 v[202:203], v[212:213], v[202:203] op_sel_hi:[0,1]
	v_pk_fma_f32 v[202:203], v[104:105], v[202:203], v[116:117]
	v_pk_fma_f32 v[140:141], v[140:141], v[200:201], v[202:203]
	v_lshlrev_b32_e32 v202, 16, v165
	v_and_b32_e32 v203, 0xffff0000, v165
	v_lshlrev_b32_e32 v200, 16, v185
	v_and_b32_e32 v201, 0xffff0000, v185
	v_pk_add_f32 v[202:203], v[202:203], v[210:211] op_sel_hi:[1,0] neg_lo:[0,1] neg_hi:[0,1]
	v_pk_mul_f32 v[202:203], v[212:213], v[202:203] op_sel_hi:[0,1]
	v_pk_fma_f32 v[202:203], v[106:107], v[202:203], v[118:119]
	v_pk_fma_f32 v[142:143], v[142:143], v[200:201], v[202:203]
	global_store_dwordx4 v224, v[140:143], s[8:9]
	v_cvt_pk_bf16_f32 v196, v140, v141
	v_cvt_pk_bf16_f32 v197, v142, v143
	v_fma_f32 v136, -v92, v210, v136
	v_fma_f32 v137, -v93, v210, v137
	v_fma_f32 v138, -v94, v210, v138
	v_fma_f32 v139, -v95, v210, v139
	v_fma_f32 v136, v136, v212, v100
	v_fma_f32 v137, v137, v212, v101
	v_fma_f32 v138, v138, v212, v102
	v_fma_f32 v139, v139, v212, v103
	v_mul_f32_e32 v136, 0xbfb8aa3b, v136
	v_mul_f32_e32 v137, 0xbfb8aa3b, v137
	v_mul_f32_e32 v138, 0xbfb8aa3b, v138
	v_mul_f32_e32 v139, 0xbfb8aa3b, v139
	v_exp_f32_e32 v136, v136
	v_exp_f32_e32 v137, v137
	v_exp_f32_e32 v138, v138
	v_exp_f32_e32 v139, v139
	v_add_f32_e32 v136, 1.0, v136
	v_add_f32_e32 v137, 1.0, v137
	v_add_f32_e32 v138, 1.0, v138
	v_add_f32_e32 v139, 1.0, v139
	v_rcp_f32_e32 v136, v136
	v_rcp_f32_e32 v137, v137
	v_rcp_f32_e32 v138, v138
	v_rcp_f32_e32 v139, v139
	v_lshlrev_b32_e32 v202, 16, v166
	v_and_b32_e32 v203, 0xffff0000, v166
	v_lshlrev_b32_e32 v200, 16, v186
	v_and_b32_e32 v201, 0xffff0000, v186
	v_pk_add_f32 v[202:203], v[202:203], v[210:211] op_sel_hi:[1,0] neg_lo:[0,1] neg_hi:[0,1]
	v_pk_mul_f32 v[202:203], v[212:213], v[202:203] op_sel_hi:[0,1]
	v_pk_fma_f32 v[202:203], v[108:109], v[202:203], v[124:125]
	v_pk_fma_f32 v[136:137], v[136:137], v[200:201], v[202:203]
	v_lshlrev_b32_e32 v202, 16, v167
	v_and_b32_e32 v203, 0xffff0000, v167
	v_lshlrev_b32_e32 v200, 16, v187
	v_and_b32_e32 v201, 0xffff0000, v187
	v_pk_add_f32 v[202:203], v[202:203], v[210:211] op_sel_hi:[1,0] neg_lo:[0,1] neg_hi:[0,1]
	v_pk_mul_f32 v[202:203], v[212:213], v[202:203] op_sel_hi:[0,1]
	v_pk_fma_f32 v[202:203], v[110:111], v[202:203], v[126:127]
	v_pk_fma_f32 v[138:139], v[138:139], v[200:201], v[202:203]
	global_store_dwordx4 v224, v[136:139], s[8:9] offset:16
	v_cvt_pk_bf16_f32 v198, v136, v137
	v_cvt_pk_bf16_f32 v199, v138, v139
	s_and_b64 vcc, exec, s[2:3]
	s_cbranch_vccz .Lpg_nx_2
	global_store_dwordx4 v226, v[196:199], s[90:91]
.Lpg_nx_2:
	v_mov_b32_e32 v226, v204
	v_add_u32_e32 v204, 0x50000, v204
	global_load_dwordx2 v[160:161], v209, s[94:95] offset:1024
	global_load_dwordx4 v[164:167], v204, s[82:83]
	global_load_dwordx4 v[184:187], v204, s[92:93]
	s_and_b64 vcc, exec, s[2:3]
	s_cbranch_vccz .Lpg_w2_3
	s_waitcnt vmcnt(6)
	s_branch .Lpg_wd_3

; __device__ __forceinline__ unsigned cvt_pk_bf16(float lo, float hi) { unsigned r; asm volatile("v_cvt_pk_bf16_f32 %0, %1, %2" : "=v"(r) : "v"(lo), "v"(hi)); return r; }
; __device__ __forceinline__ float bf_lo(unsigned w) { return __uint_as_float(w << 16); }
; __device__ __forceinline__ float bf_hi(unsigned w) { return __uint_as_float(w & 0xffff0000u); }
;     __device__ __forceinline__ void operator()(const f32x4 (&acc)[2][2][4][2], const Unit& u, int wr, int wc, int fr, int fq) const {
;     ...
;         for (int bj = 0; bj < 2; ++bj) { const int col = col0 + bj * HALF;
;             f32x4 c1[2], c2[2], lg[2], lb[2];
; #pragma unroll
;             for (int n = 0; n < 2; ++n) { c1[n] = *(const f32x4*)(C1 + col + 4 * n); c2[n] = *(const f32x4*)(C2 + col + 4 * n); lg[n] = *(const f32x4*)(LG + col + 4 * n); lb[n] = *(const f32x4*)(LB + col + 4 * n); }
; #pragma unroll
;             for (int ai = 0; ai < 2; ++ai)
; #pragma unroll
;                 for (int m = 0; m < 4; ++m) { const int row = row0 + ai * HALF + m * 16; const size_t o2 = (size_t)row * ldc + col;
;                     const float s1 = ST[2 * row], s2 = ST[2 * row + 1], mu = s1 * (1.f / 2048.f), rstd = __builtin_amdgcn_rsqf(fmaxf(s2 * (1.f / 2048.f) - mu * mu, 0.f) + 1e-5f);
;                     const u32x4 zw = *(const u32x4*)(Zb + o2), pw = *(const u32x4*)(PE + o2); u32x4 xw;
; #pragma unroll
;                     for (int n = 0; n < 2; ++n) { const unsigned za = n ? zw.z : zw.x, zb2 = n ? zw.w : zw.y, pa = n ? pw.z : pw.x, pb = n ? pw.w : pw.y;
;                         const float zv[4] = {bf_lo(za), bf_hi(za), bf_lo(zb2), bf_hi(zb2)}, pv[4] = {bf_lo(pa), bf_hi(pa), bf_lo(pb), bf_hi(pb)}; const f32x4 a = acc[ai][bj][m][n]; f32x4 o;
; #pragma unroll
;                         for (int e = 0; e < 4; ++e) { const float sv = rstd * (a[e] - mu * c1[n][e]) + c2[n][e]; const float xl = (zv[e] - mu) * rstd * lg[n][e] + lb[n][e]; o[e] = xl + pv[e] * __builtin_amdgcn_rcpf(1.f + __expf(-sv)); }
;                         *(f32x4*)(OUTF + o2 + 4 * n) = o; if (n == 0) { xw.x = cvt_pk_bf16(o[0], o[1]); xw.y = cvt_pk_bf16(o[2], o[3]); } else { xw.z = cvt_pk_bf16(o[0], o[1]); xw.w = cvt_pk_bf16(o[2], o[3]); } }
;                     if (XB) *(u32x4*)(XB + o2) = xw; }
.Lpg_wd_3:
	v_pk_mul_f32 v[210:211], v[162:163], s[0:1] op_sel_hi:[1,0]
	v_lshlrev_b32_e32 v224, 1, v226
	v_fma_f32 v212, -v210, v210, v211
	v_max_f32_e32 v212, 0, v212
	v_add_f32_e32 v212, 0x3727c5ac, v212
	v_rsq_f32_e32 v212, v212
	v_fma_f32 v132, -v88, v210, v132
	v_fma_f32 v133, -v89, v210, v133
	v_fma_f32 v134, -v90, v210, v134
	v_fma_f32 v135, -v91, v210, v135
	v_fma_f32 v132, v132, v212, v96
	v_fma_f32 v133, v133, v212, v97
	v_fma_f32 v134, v134, v212, v98
	v_fma_f32 v135, v135, v212, v99
	v_mul_f32_e32 v132, 0xbfb8aa3b, v132
	v_mul_f32_e32 v133, 0xbfb8aa3b, v133
	v_mul_f32_e32 v134, 0xbfb8aa3b, v134
	v_mul_f32_e32 v135, 0xbfb8aa3b, v135
	v_exp_f32_e32 v132, v132
	v_exp_f32_e32 v133, v133
	v_exp_f32_e32 v134, v134
	v_exp_f32_e32 v135, v135
	v_add_f32_e32 v132, 1.0, v132
	v_add_f32_e32 v133, 1.0, v133
	v_add_f32_e32 v134, 1.0, v134
	v_add_f32_e32 v135, 1.0, v135
	v_rcp_f32_e32 v132, v132
	v_rcp_f32_e32 v133, v133
	v_rcp_f32_e32 v134, v134
	v_rcp_f32_e32 v135, v135
	v_lshlrev_b32_e32 v202, 16, v188
	v_and_b32_e32 v203, 0xffff0000, v188
	v_lshlrev_b32_e32 v200, 16, v192
	v_and_b32_e32 v201, 0xffff0000, v192
	v_pk_add_f32 v[202:203], v[202:203], v[210:211] op_sel_hi:[1,0] neg_lo:[0,1] neg_hi:[0,1]
	v_pk_mul_f32 v[202:203], v[212:213], v[202:203] op_sel_hi:[0,1]
	v_pk_fma_f32 v[202:203], v[104:105], v[202:203], v[116:117]
	v_pk_fma_f32 v[132:133], v[132:133], v[200:201], v[202:203]
	v_lshlrev_b32_e32 v202, 16, v189
	v_and_b32_e32 v203, 0xffff0000, v189
	v_lshlrev_b32_e32 v200, 16, v193
	v_and_b32_e32 v201, 0xffff0000, v193
	v_pk_add_f32 v[202:203], v[202:203], v[210:211] op_sel_hi:[1,0] neg_lo:[0,1] neg_hi:[0,1]
	v_pk_mul_f32 v[202:203], v[212:213], v[202:203] op_sel_hi:[0,1]
	v_pk_fma_f32 v[202:203], v[106:107], v[202:203], v[118:119]
	v_pk_fma_f32 v[134:135], v[134:135], v[200:201], v[202:203]
	global_store_dwordx4 v224, v[132:135], s[8:9]
	v_cvt_pk_bf16_f32 v196, v132, v133
	v_cvt_pk_bf16_f32 v197, v134, v135
	v_fma_f32 v128, -v92, v210, v128
	v_fma_f32 v129, -v93, v210, v129
	v_fma_f32 v130, -v94, v210, v130
	v_fma_f32 v131, -v95, v210, v131
	v_fma_f32 v128, v128, v212, v100
	v_fma_f32 v129, v129, v212, v101
	v_fma_f32 v130, v130, v212, v102
	v_fma_f32 v131, v131, v212, v103
	v_mul_f32_e32 v128, 0xbfb8aa3b, v128
	v_mul_f32_e32 v129, 0xbfb8aa3b, v129
	v_mul_f32_e32 v130, 0xbfb8aa3b, v130
	v_mul_f32_e32 v131, 0xbfb8aa3b, v131
	v_exp_f32_e32 v128, v128
	v_exp_f32_e32 v129, v129
	v_exp_f32_e32 v130, v130
	v_exp_f32_e32 v131, v131
	v_add_f32_e32 v128, 1.0, v128
	v_add_f32_e32 v129, 1.0, v129
	v_add_f32_e32 v130, 1.0, v130
	v_add_f32_e32 v131, 1.0, v131
	v_rcp_f32_e32 v128, v128
	v_rcp_f32_e32 v129, v129
	v_rcp_f32_e32 v130, v130
	v_rcp_f32_e32 v131, v131
	v_lshlrev_b32_e32 v202, 16, v190
	v_and_b32_e32 v203, 0xffff0000, v190
	v_lshlrev_b32_e32 v200, 16, v194
	v_and_b32_e32 v201, 0xffff0000, v194
	v_pk_add_f32 v[202:203], v[202:203], v[210:211] op_sel_hi:[1,0] neg_lo:[0,1] neg_hi:[0,1]
	v_pk_mul_f32 v[202:203], v[212:213], v[202:203] op_sel_hi:[0,1]
	v_pk_fma_f32 v[202:203], v[108:109], v[202:203], v[124:125]
	v_pk_fma_f32 v[128:129], v[128:129], v[200:201], v[202:203]
	v_lshlrev_b32_e32 v202, 16, v191
	v_and_b32_e32 v203, 0xffff0000, v191
	v_lshlrev_b32_e32 v200, 16, v195
	v_and_b32_e32 v201, 0xffff0000, v195
	v_pk_add_f32 v[202:203], v[202:203], v[210:211] op_sel_hi:[1,0] neg_lo:[0,1] neg_hi:[0,1]
	v_pk_mul_f32 v[202:203], v[212:213], v[202:203] op_sel_hi:[0,1]
	v_pk_fma_f32 v[202:203], v[110:111], v[202:203], v[126:127]
	v_pk_fma_f32 v[130:131], v[130:131], v[200:201], v[202:203]
	global_store_dwordx4 v224, v[128:131], s[8:9] offset:16
	v_cvt_pk_bf16_f32 v198, v128, v129
	v_cvt_pk_bf16_f32 v199, v130, v131
	s_and_b64 vcc, exec, s[2:3]
	s_cbranch_vccz .Lpg_nx_3
	global_store_dwordx4 v226, v[196:199], s[90:91]
.Lpg_nx_3:
	v_mov_b32_e32 v226, v204
	v_add_u32_e32 v204, 0x10000, v204
	global_load_dwordx2 v[162:163], v209, s[94:95] offset:1152
	global_load_dwordx4 v[188:191], v204, s[82:83]
	global_load_dwordx4 v[192:195], v204, s[92:93]
	s_and_b64 vcc, exec, s[2:3]
	s_cbranch_vccz .Lpg_w2_4
	s_waitcnt vmcnt(6)
	s_branch .Lpg_wd_4

; __device__ __forceinline__ unsigned cvt_pk_bf16(float lo, float hi) { unsigned r; asm volatile("v_cvt_pk_bf16_f32 %0, %1, %2" : "=v"(r) : "v"(lo), "v"(hi)); return r; }
; __device__ __forceinline__ float bf_lo(unsigned w) { return __uint_as_float(w << 16); }
; __device__ __forceinline__ float bf_hi(unsigned w) { return __uint_as_float(w & 0xffff0000u); }
;     __device__ __forceinline__ void operator()(const f32x4 (&acc)[2][2][4][2], const Unit& u, int wr, int wc, int fr, int fq) const {
;     ...
;         for (int bj = 0; bj < 2; ++bj) { const int col = col0 + bj * HALF;
;             f32x4 c1[2], c2[2], lg[2], lb[2];
; #pragma unroll
;             for (int n = 0; n < 2; ++n) { c1[n] = *(const f32x4*)(C1 + col + 4 * n); c2[n] = *(const f32x4*)(C2 + col + 4 * n); lg[n] = *(const f32x4*)(LG + col + 4 * n); lb[n] = *(const f32x4*)(LB + col + 4 * n); }
; #pragma unroll
;             for (int ai = 0; ai < 2; ++ai)
; #pragma unroll
;                 for (int m = 0; m < 4; ++m) { const int row = row0 + ai * HALF + m * 16; const size_t o2 = (size_t)row * ldc + col;
;                     const float s1 = ST[2 * row], s2 = ST[2 * row + 1], mu = s1 * (1.f / 2048.f), rstd = __builtin_amdgcn_rsqf(fmaxf(s2 * (1.f / 2048.f) - mu * mu, 0.f) + 1e-5f);
;                     const u32x4 zw = *(const u32x4*)(Zb + o2), pw = *(const u32x4*)(PE + o2); u32x4 xw;
; #pragma unroll
;                     for (int n = 0; n < 2; ++n) { const unsigned za = n ? zw.z : zw.x, zb2 = n ? zw.w : zw.y, pa = n ? pw.z : pw.x, pb = n ? pw.w : pw.y;
;                         const float zv[4] = {bf_lo(za), bf_hi(za), bf_lo(zb2), bf_hi(zb2)}, pv[4] = {bf_lo(pa), bf_hi(pa), bf_lo(pb), bf_hi(pb)}; const f32x4 a = acc[ai][bj][m][n]; f32x4 o;
; #pragma unroll
;                         for (int e = 0; e < 4; ++e) { const float sv = rstd * (a[e] - mu * c1[n][e]) + c2[n][e]; const float xl = (zv[e] - mu) * rstd * lg[n][e] + lb[n][e]; o[e] = xl + pv[e] * __builtin_amdgcn_rcpf(1.f + __expf(-sv)); }
;                         *(f32x4*)(OUTF + o2 + 4 * n) = o; if (n == 0) { xw.x = cvt_pk_bf16(o[0], o[1]); xw.y = cvt_pk_bf16(o[2], o[3]); } else { xw.z = cvt_pk_bf16(o[0], o[1]); xw.w = cvt_pk_bf16(o[2], o[3]); } }
;                     if (XB) *(u32x4*)(XB + o2) = xw; }
.Lpg_wd_4:
	v_pk_mul_f32 v[210:211], v[160:161], s[0:1] op_sel_hi:[1,0]
	v_lshlrev_b32_e32 v224, 1, v226
	v_fma_f32 v212, -v210, v210, v211
	v_max_f32_e32 v212, 0, v212
	v_add_f32_e32 v212, 0x3727c5ac, v212
	v_rsq_f32_e32 v212, v212
	v_fma_f32 v120, -v88, v210, v120
	v_fma_f32 v121, -v89, v210, v121
	v_fma_f32 v122, -v90, v210, v122
	v_fma_f32 v123, -v91, v210, v123
	v_fma_f32 v120, v120, v212, v96
	v_fma_f32 v121, v121, v212, v97
	v_fma_f32 v122, v122, v212, v98
	v_fma_f32 v123, v123, v212, v99
	v_mul_f32_e32 v120, 0xbfb8aa3b, v120
	v_mul_f32_e32 v121, 0xbfb8aa3b, v121
	v_mul_f32_e32 v122, 0xbfb8aa3b, v122
	v_mul_f32_e32 v123, 0xbfb8aa3b, v123
	v_exp_f32_e32 v120, v120
	v_exp_f32_e32 v121, v121
	v_exp_f32_e32 v122, v122
	v_exp_f32_e32 v123, v123
	v_add_f32_e32 v120, 1.0, v120
	v_add_f32_e32 v121, 1.0, v121
	v_add_f32_e32 v122, 1.0, v122
	v_add_f32_e32 v123, 1.0, v123
	v_rcp_f32_e32 v120, v120
	v_rcp_f32_e32 v121, v121
	v_rcp_f32_e32 v122, v122
	v_rcp_f32_e32 v123, v123
	v_lshlrev_b32_e32 v202, 16, v164
	v_and_b32_e32 v203, 0xffff0000, v164
	v_lshlrev_b32_e32 v200, 16, v184
	v_and_b32_e32 v201, 0xffff0000, v184
	v_pk_add_f32 v[202:203], v[202:203], v[210:211] op_sel_hi:[1,0] neg_lo:[0,1] neg_hi:[0,1]
	v_pk_mul_f32 v[202:203], v[212:213], v[202:203] op_sel_hi:[0,1]
	v_pk_fma_f32 v[202:203], v[104:105], v[202:203], v[116:117]
	v_pk_fma_f32 v[120:121], v[120:121], v[200:201], v[202:203]
	v_lshlrev_b32_e32 v202, 16, v165
	v_and_b32_e32 v203, 0xffff0000, v165
	v_lshlrev_b32_e32 v200, 16, v185
	v_and_b32_e32 v201, 0xffff0000, v185
	v_pk_add_f32 v[202:203], v[202:203], v[210:211] op_sel_hi:[1,0] neg_lo:[0,1] neg_hi:[0,1]
	v_pk_mul_f32 v[202:203], v[212:213], v[202:203] op_sel_hi:[0,1]
	v_pk_fma_f32 v[202:203], v[106:107], v[202:203], v[118:119]
	v_pk_fma_f32 v[122:123], v[122:123], v[200:201], v[202:203]
	global_store_dwordx4 v224, v[120:123], s[8:9]
	v_cvt_pk_bf16_f32 v196, v120, v121
	v_cvt_pk_bf16_f32 v197, v122, v123
	v_fma_f32 v112, -v92, v210, v112
	v_fma_f32 v113, -v93, v210, v113
	v_fma_f32 v114, -v94, v210, v114
	v_fma_f32 v115, -v95, v210, v115
	v_fma_f32 v112, v112, v212, v100
	v_fma_f32 v113, v113, v212, v101
	v_fma_f32 v114, v114, v212, v102
	v_fma_f32 v115, v115, v212, v103
	v_mul_f32_e32 v112, 0xbfb8aa3b, v112
	v_mul_f32_e32 v113, 0xbfb8aa3b, v113
	v_mul_f32_e32 v114, 0xbfb8aa3b, v114
	v_mul_f32_e32 v115, 0xbfb8aa3b, v115
	v_exp_f32_e32 v112, v112
	v_exp_f32_e32 v113, v113
	v_exp_f32_e32 v114, v114
	v_exp_f32_e32 v115, v115
	v_add_f32_e32 v112, 1.0, v112
	v_add_f32_e32 v113, 1.0, v113
	v_add_f32_e32 v114, 1.0, v114
	v_add_f32_e32 v115, 1.0, v115
	v_rcp_f32_e32 v112, v112
	v_rcp_f32_e32 v113, v113
	v_rcp_f32_e32 v114, v114
	v_rcp_f32_e32 v115, v115
	v_lshlrev_b32_e32 v202, 16, v166
	v_and_b32_e32 v203, 0xffff0000, v166
	v_lshlrev_b32_e32 v200, 16, v186
	v_and_b32_e32 v201, 0xffff0000, v186
	v_pk_add_f32 v[202:203], v[202:203], v[210:211] op_sel_hi:[1,0] neg_lo:[0,1] neg_hi:[0,1]
	v_pk_mul_f32 v[202:203], v[212:213], v[202:203] op_sel_hi:[0,1]
	v_pk_fma_f32 v[202:203], v[108:109], v[202:203], v[124:125]
	v_pk_fma_f32 v[112:113], v[112:113], v[200:201], v[202:203]
	v_lshlrev_b32_e32 v202, 16, v167
	v_and_b32_e32 v203, 0xffff0000, v167
	v_lshlrev_b32_e32 v200, 16, v187
	v_and_b32_e32 v201, 0xffff0000, v187
	v_pk_add_f32 v[202:203], v[202:203], v[210:211] op_sel_hi:[1,0] neg_lo:[0,1] neg_hi:[0,1]
	v_pk_mul_f32 v[202:203], v[212:213], v[202:203] op_sel_hi:[0,1]
	v_pk_fma_f32 v[202:203], v[110:111], v[202:203], v[126:127]
	v_pk_fma_f32 v[114:115], v[114:115], v[200:201], v[202:203]
	global_store_dwordx4 v224, v[112:115], s[8:9] offset:16
	v_cvt_pk_bf16_f32 v198, v112, v113
	v_cvt_pk_bf16_f32 v199, v114, v115
	s_and_b64 vcc, exec, s[2:3]
	s_cbranch_vccz .Lpg_nx_4
	global_store_dwordx4 v226, v[196:199], s[90:91]
.Lpg_nx_4:
	v_mov_b32_e32 v226, v204
	v_add_u32_e32 v204, 0x10000, v204
	global_load_dwordx2 v[160:161], v209, s[94:95] offset:1280
	global_load_dwordx4 v[164:167], v204, s[82:83]
	global_load_dwordx4 v[184:187], v204, s[92:93]
	s_and_b64 vcc, exec, s[2:3]
	s_cbranch_vccz .Lpg_w2_5
	s_waitcnt vmcnt(6)
	s_branch .Lpg_wd_5

; __device__ __forceinline__ unsigned cvt_pk_bf16(float lo, float hi) { unsigned r; asm volatile("v_cvt_pk_bf16_f32 %0, %1, %2" : "=v"(r) : "v"(lo), "v"(hi)); return r; }
; __device__ __forceinline__ float bf_lo(unsigned w) { return __uint_as_float(w << 16); }
; __device__ __forceinline__ float bf_hi(unsigned w) { return __uint_as_float(w & 0xffff0000u); }
;     __device__ __forceinline__ void operator()(const f32x4 (&acc)[2][2][4][2], const Unit& u, int wr, int wc, int fr, int fq) const {
;     ...
;         for (int bj = 0; bj < 2; ++bj) { const int col = col0 + bj * HALF;
;             f32x4 c1[2], c2[2], lg[2], lb[2];
; #pragma unroll
;             for (int n = 0; n < 2; ++n) { c1[n] = *(const f32x4*)(C1 + col + 4 * n); c2[n] = *(const f32x4*)(C2 + col + 4 * n); lg[n] = *(const f32x4*)(LG + col + 4 * n); lb[n] = *(const f32x4*)(LB + col + 4 * n); }
; #pragma unroll
;             for (int ai = 0; ai < 2; ++ai)
; #pragma unroll
;                 for (int m = 0; m < 4; ++m) { const int row = row0 + ai * HALF + m * 16; const size_t o2 = (size_t)row * ldc + col;
;                     const float s1 = ST[2 * row], s2 = ST[2 * row + 1], mu = s1 * (1.f / 2048.f), rstd = __builtin_amdgcn_rsqf(fmaxf(s2 * (1.f / 2048.f) - mu * mu, 0.f) + 1e-5f);
;                     const u32x4 zw = *(const u32x4*)(Zb + o2), pw = *(const u32x4*)(PE + o2); u32x4 xw;
; #pragma unroll
;                     for (int n = 0; n < 2; ++n) { const unsigned za = n ? zw.z : zw.x, zb2 = n ? zw.w : zw.y, pa = n ? pw.z : pw.x, pb = n ? pw.w : pw.y;
;                         const float zv[4] = {bf_lo(za), bf_hi(za), bf_lo(zb2), bf_hi(zb2)}, pv[4] = {bf_lo(pa), bf_hi(pa), bf_lo(pb), bf_hi(pb)}; const f32x4 a = acc[ai][bj][m][n]; f32x4 o;
; #pragma unroll
;                         for (int e = 0; e < 4; ++e) { const float sv = rstd * (a[e] - mu * c1[n][e]) + c2[n][e]; const float xl = (zv[e] - mu) * rstd * lg[n][e] + lb[n][e]; o[e] = xl + pv[e] * __builtin_amdgcn_rcpf(1.f + __expf(-sv)); }
;                         *(f32x4*)(OUTF + o2 + 4 * n) = o; if (n == 0) { xw.x = cvt_pk_bf16(o[0], o[1]); xw.y = cvt_pk_bf16(o[2], o[3]); } else { xw.z = cvt_pk_bf16(o[0], o[1]); xw.w = cvt_pk_bf16(o[2], o[3]); } }
;                     if (XB) *(u32x4*)(XB + o2) = xw; }
.Lpg_wd_5:
	v_pk_mul_f32 v[210:211], v[162:163], s[0:1] op_sel_hi:[1,0]
	v_lshlrev_b32_e32 v224, 1, v226
	v_fma_f32 v212, -v210, v210, v211
	v_max_f32_e32 v212, 0, v212
	v_add_f32_e32 v212, 0x3727c5ac, v212
	v_rsq_f32_e32 v212, v212
	v_fma_f32 v84, -v88, v210, v84
	v_fma_f32 v85, -v89, v210, v85
	v_fma_f32 v86, -v90, v210, v86
	v_fma_f32 v87, -v91, v210, v87
	v_fma_f32 v84, v84, v212, v96
	v_fma_f32 v85, v85, v212, v97
	v_fma_f32 v86, v86, v212, v98
	v_fma_f32 v87, v87, v212, v99
	v_mul_f32_e32 v84, 0xbfb8aa3b, v84
	v_mul_f32_e32 v85, 0xbfb8aa3b, v85
	v_mul_f32_e32 v86, 0xbfb8aa3b, v86
	v_mul_f32_e32 v87, 0xbfb8aa3b, v87
	v_exp_f32_e32 v84, v84
	v_exp_f32_e32 v85, v85
	v_exp_f32_e32 v86, v86
	v_exp_f32_e32 v87, v87
	v_add_f32_e32 v84, 1.0, v84
	v_add_f32_e32 v85, 1.0, v85
	v_add_f32_e32 v86, 1.0, v86
	v_add_f32_e32 v87, 1.0, v87
	v_rcp_f32_e32 v84, v84
	v_rcp_f32_e32 v85, v85
	v_rcp_f32_e32 v86, v86
	v_rcp_f32_e32 v87, v87
	v_lshlrev_b32_e32 v202, 16, v188
	v_and_b32_e32 v203, 0xffff0000, v188
	v_lshlrev_b32_e32 v200, 16, v192
	v_and_b32_e32 v201, 0xffff0000, v192
	v_pk_add_f32 v[202:203], v[202:203], v[210:211] op_sel_hi:[1,0] neg_lo:[0,1] neg_hi:[0,1]
	v_pk_mul_f32 v[202:203], v[212:213], v[202:203] op_sel_hi:[0,1]
	v_pk_fma_f32 v[202:203], v[104:105], v[202:203], v[116:117]
	v_pk_fma_f32 v[84:85], v[84:85], v[200:201], v[202:203]
	v_lshlrev_b32_e32 v202, 16, v189
	v_and_b32_e32 v203, 0xffff0000, v189
	v_lshlrev_b32_e32 v200, 16, v193
	v_and_b32_e32 v201, 0xffff0000, v193
	v_pk_add_f32 v[202:203], v[202:203], v[210:211] op_sel_hi:[1,0] neg_lo:[0,1] neg_hi:[0,1]
	v_pk_mul_f32 v[202:203], v[212:213], v[202:203] op_sel_hi:[0,1]
	v_pk_fma_f32 v[202:203], v[106:107], v[202:203], v[118:119]
	v_pk_fma_f32 v[86:87], v[86:87], v[200:201], v[202:203]
	global_store_dwordx4 v224, v[84:87], s[8:9]
	v_cvt_pk_bf16_f32 v196, v84, v85
	v_cvt_pk_bf16_f32 v197, v86, v87
	v_fma_f32 v80, -v92, v210, v80
	v_fma_f32 v81, -v93, v210, v81
	v_fma_f32 v82, -v94, v210, v82
	v_fma_f32 v83, -v95, v210, v83
	v_fma_f32 v80, v80, v212, v100
	v_fma_f32 v81, v81, v212, v101
	v_fma_f32 v82, v82, v212, v102
	v_fma_f32 v83, v83, v212, v103
	v_mul_f32_e32 v80, 0xbfb8aa3b, v80
	v_mul_f32_e32 v81, 0xbfb8aa3b, v81
	v_mul_f32_e32 v82, 0xbfb8aa3b, v82
	v_mul_f32_e32 v83, 0xbfb8aa3b, v83
	v_exp_f32_e32 v80, v80
	v_exp_f32_e32 v81, v81
	v_exp_f32_e32 v82, v82
	v_exp_f32_e32 v83, v83
	v_add_f32_e32 v80, 1.0, v80
	v_add_f32_e32 v81, 1.0, v81
	v_add_f32_e32 v82, 1.0, v82
	v_add_f32_e32 v83, 1.0, v83
	v_rcp_f32_e32 v80, v80
	v_rcp_f32_e32 v81, v81
	v_rcp_f32_e32 v82, v82
	v_rcp_f32_e32 v83, v83
	v_lshlrev_b32_e32 v202, 16, v190
	v_and_b32_e32 v203, 0xffff0000, v190
	v_lshlrev_b32_e32 v200, 16, v194
	v_and_b32_e32 v201, 0xffff0000, v194
	v_pk_add_f32 v[202:203], v[202:203], v[210:211] op_sel_hi:[1,0] neg_lo:[0,1] neg_hi:[0,1]
	v_pk_mul_f32 v[202:203], v[212:213], v[202:203] op_sel_hi:[0,1]
	v_pk_fma_f32 v[202:203], v[108:109], v[202:203], v[124:125]
	v_pk_fma_f32 v[80:81], v[80:81], v[200:201], v[202:203]
	v_lshlrev_b32_e32 v202, 16, v191
	v_and_b32_e32 v203, 0xffff0000, v191
	v_lshlrev_b32_e32 v200, 16, v195
	v_and_b32_e32 v201, 0xffff0000, v195
	v_pk_add_f32 v[202:203], v[202:203], v[210:211] op_sel_hi:[1,0] neg_lo:[0,1] neg_hi:[0,1]
	v_pk_mul_f32 v[202:203], v[212:213], v[202:203] op_sel_hi:[0,1]
	v_pk_fma_f32 v[202:203], v[110:111], v[202:203], v[126:127]
	v_pk_fma_f32 v[82:83], v[82:83], v[200:201], v[202:203]
	global_store_dwordx4 v224, v[80:83], s[8:9] offset:16
	v_cvt_pk_bf16_f32 v198, v80, v81
	v_cvt_pk_bf16_f32 v199, v82, v83
	s_and_b64 vcc, exec, s[2:3]
	s_cbranch_vccz .Lpg_nx_5
	global_store_dwordx4 v226, v[196:199], s[90:91]
.Lpg_nx_5:
	v_mov_b32_e32 v226, v204
	v_add_u32_e32 v204, 0x10000, v204
	global_load_dwordx2 v[162:163], v209, s[94:95] offset:1408
	global_load_dwordx4 v[188:191], v204, s[82:83]
	global_load_dwordx4 v[192:195], v204, s[92:93]
	s_and_b64 vcc, exec, s[2:3]
	s_cbranch_vccz .Lpg_w2_6
	s_waitcnt vmcnt(6)
	s_branch .Lpg_wd_6

; __device__ __forceinline__ unsigned cvt_pk_bf16(float lo, float hi) { unsigned r; asm volatile("v_cvt_pk_bf16_f32 %0, %1, %2" : "=v"(r) : "v"(lo), "v"(hi)); return r; }
; __device__ __forceinline__ float bf_lo(unsigned w) { return __uint_as_float(w << 16); }
; __device__ __forceinline__ float bf_hi(unsigned w) { return __uint_as_float(w & 0xffff0000u); }
;     __device__ __forceinline__ void operator()(const f32x4 (&acc)[2][2][4][2], const Unit& u, int wr, int wc, int fr, int fq) const {
;     ...
;         for (int bj = 0; bj < 2; ++bj) { const int col = col0 + bj * HALF;
;             f32x4 c1[2], c2[2], lg[2], lb[2];
; #pragma unroll
;             for (int n = 0; n < 2; ++n) { c1[n] = *(const f32x4*)(C1 + col + 4 * n); c2[n] = *(const f32x4*)(C2 + col + 4 * n); lg[n] = *(const f32x4*)(LG + col + 4 * n); lb[n] = *(const f32x4*)(LB + col + 4 * n); }
; #pragma unroll
;             for (int ai = 0; ai < 2; ++ai)
; #pragma unroll
;                 for (int m = 0; m < 4; ++m) { const int row = row0 + ai * HALF + m * 16; const size_t o2 = (size_t)row * ldc + col;
;                     const float s1 = ST[2 * row], s2 = ST[2 * row + 1], mu = s1 * (1.f / 2048.f), rstd = __builtin_amdgcn_rsqf(fmaxf(s2 * (1.f / 2048.f) - mu * mu, 0.f) + 1e-5f);
;                     const u32x4 zw = *(const u32x4*)(Zb + o2), pw = *(const u32x4*)(PE + o2); u32x4 xw;
; #pragma unroll
;                     for (int n = 0; n < 2; ++n) { const unsigned za = n ? zw.z : zw.x, zb2 = n ? zw.w : zw.y, pa = n ? pw.z : pw.x, pb = n ? pw.w : pw.y;
;                         const float zv[4] = {bf_lo(za), bf_hi(za), bf_lo(zb2), bf_hi(zb2)}, pv[4] = {bf_lo(pa), bf_hi(pa), bf_lo(pb), bf_hi(pb)}; const f32x4 a = acc[ai][bj][m][n]; f32x4 o;
; #pragma unroll
;                         for (int e = 0; e < 4; ++e) { const float sv = rstd * (a[e] - mu * c1[n][e]) + c2[n][e]; const float xl = (zv[e] - mu) * rstd * lg[n][e] + lb[n][e]; o[e] = xl + pv[e] * __builtin_amdgcn_rcpf(1.f + __expf(-sv)); }
;                         *(f32x4*)(OUTF + o2 + 4 * n) = o; if (n == 0) { xw.x = cvt_pk_bf16(o[0], o[1]); xw.y = cvt_pk_bf16(o[2], o[3]); } else { xw.z = cvt_pk_bf16(o[0], o[1]); xw.w = cvt_pk_bf16(o[2], o[3]); } }
;                     if (XB) *(u32x4*)(XB + o2) = xw; }
.Lpg_wd_6:
	v_pk_mul_f32 v[210:211], v[160:161], s[0:1] op_sel_hi:[1,0]
	v_lshlrev_b32_e32 v224, 1, v226
	v_fma_f32 v212, -v210, v210, v211
	v_max_f32_e32 v212, 0, v212
	v_add_f32_e32 v212, 0x3727c5ac, v212
	v_rsq_f32_e32 v212, v212
	v_fma_f32 v76, -v88, v210, v76
	v_fma_f32 v77, -v89, v210, v77
	v_fma_f32 v78, -v90, v210, v78
	v_fma_f32 v79, -v91, v210, v79
	v_fma_f32 v76, v76, v212, v96
	v_fma_f32 v77, v77, v212, v97
	v_fma_f32 v78, v78, v212, v98
	v_fma_f32 v79, v79, v212, v99
	v_mul_f32_e32 v76, 0xbfb8aa3b, v76
	v_mul_f32_e32 v77, 0xbfb8aa3b, v77
	v_mul_f32_e32 v78, 0xbfb8aa3b, v78
	v_mul_f32_e32 v79, 0xbfb8aa3b, v79
	v_exp_f32_e32 v76, v76
	v_exp_f32_e32 v77, v77
	v_exp_f32_e32 v78, v78
	v_exp_f32_e32 v79, v79
	v_add_f32_e32 v76, 1.0, v76
	v_add_f32_e32 v77, 1.0, v77
	v_add_f32_e32 v78, 1.0, v78
	v_add_f32_e32 v79, 1.0, v79
	v_rcp_f32_e32 v76, v76
	v_rcp_f32_e32 v77, v77
	v_rcp_f32_e32 v78, v78
	v_rcp_f32_e32 v79, v79
	v_lshlrev_b32_e32 v202, 16, v164
	v_and_b32_e32 v203, 0xffff0000, v164
	v_lshlrev_b32_e32 v200, 16, v184
	v_and_b32_e32 v201, 0xffff0000, v184
	v_pk_add_f32 v[202:203], v[202:203], v[210:211] op_sel_hi:[1,0] neg_lo:[0,1] neg_hi:[0,1]
	v_pk_mul_f32 v[202:203], v[212:213], v[202:203] op_sel_hi:[0,1]
	v_pk_fma_f32 v[202:203], v[104:105], v[202:203], v[116:117]
	v_pk_fma_f32 v[76:77], v[76:77], v[200:201], v[202:203]
	v_lshlrev_b32_e32 v202, 16, v165
	v_and_b32_e32 v203, 0xffff0000, v165
	v_lshlrev_b32_e32 v200, 16, v185
	v_and_b32_e32 v201, 0xffff0000, v185
	v_pk_add_f32 v[202:203], v[202:203], v[210:211] op_sel_hi:[1,0] neg_lo:[0,1] neg_hi:[0,1]
	v_pk_mul_f32 v[202:203], v[212:213], v[202:203] op_sel_hi:[0,1]
	v_pk_fma_f32 v[202:203], v[106:107], v[202:203], v[118:119]
	v_pk_fma_f32 v[78:79], v[78:79], v[200:201], v[202:203]
	global_store_dwordx4 v224, v[76:79], s[8:9]
	v_cvt_pk_bf16_f32 v196, v76, v77
	v_cvt_pk_bf16_f32 v197, v78, v79
	v_fma_f32 v72, -v92, v210, v72
	v_fma_f32 v73, -v93, v210, v73
	v_fma_f32 v74, -v94, v210, v74
	v_fma_f32 v75, -v95, v210, v75
	v_fma_f32 v72, v72, v212, v100
	v_fma_f32 v73, v73, v212, v101
	v_fma_f32 v74, v74, v212, v102
	v_fma_f32 v75, v75, v212, v103
	v_mul_f32_e32 v72, 0xbfb8aa3b, v72
	v_mul_f32_e32 v73, 0xbfb8aa3b, v73
	v_mul_f32_e32 v74, 0xbfb8aa3b, v74
	v_mul_f32_e32 v75, 0xbfb8aa3b, v75
	v_exp_f32_e32 v72, v72
	v_exp_f32_e32 v73, v73
	v_exp_f32_e32 v74, v74
	v_exp_f32_e32 v75, v75
	v_add_f32_e32 v72, 1.0, v72
	v_add_f32_e32 v73, 1.0, v73
	v_add_f32_e32 v74, 1.0, v74
	v_add_f32_e32 v75, 1.0, v75
	v_rcp_f32_e32 v72, v72
	v_rcp_f32_e32 v73, v73
	v_rcp_f32_e32 v74, v74
	v_rcp_f32_e32 v75, v75
	v_lshlrev_b32_e32 v202, 16, v166
	v_and_b32_e32 v203, 0xffff0000, v166
	v_lshlrev_b32_e32 v200, 16, v186
	v_and_b32_e32 v201, 0xffff0000, v186
	v_pk_add_f32 v[202:203], v[202:203], v[210:211] op_sel_hi:[1,0] neg_lo:[0,1] neg_hi:[0,1]
	v_pk_mul_f32 v[202:203], v[212:213], v[202:203] op_sel_hi:[0,1]
	v_pk_fma_f32 v[202:203], v[108:109], v[202:203], v[124:125]
	v_pk_fma_f32 v[72:73], v[72:73], v[200:201], v[202:203]
	v_lshlrev_b32_e32 v202, 16, v167
	v_and_b32_e32 v203, 0xffff0000, v167
	v_lshlrev_b32_e32 v200, 16, v187
	v_and_b32_e32 v201, 0xffff0000, v187
	v_pk_add_f32 v[202:203], v[202:203], v[210:211] op_sel_hi:[1,0] neg_lo:[0,1] neg_hi:[0,1]
	v_pk_mul_f32 v[202:203], v[212:213], v[202:203] op_sel_hi:[0,1]
	v_pk_fma_f32 v[202:203], v[110:111], v[202:203], v[126:127]
	v_pk_fma_f32 v[74:75], v[74:75], v[200:201], v[202:203]
	global_store_dwordx4 v224, v[72:75], s[8:9] offset:16
	v_cvt_pk_bf16_f32 v198, v72, v73
	v_cvt_pk_bf16_f32 v199, v74, v75
	s_and_b64 vcc, exec, s[2:3]
	s_cbranch_vccz .Lpg_nx_6
	global_store_dwordx4 v226, v[196:199], s[90:91]
.Lpg_nx_6:
	v_mov_b32_e32 v226, v204
	v_add_u32_e32 v204, 0xfff50100, v204
	global_load_dwordx2 v[160:161], v209, s[94:95]
	global_load_dwordx4 v[164:167], v204, s[82:83]
	global_load_dwordx4 v[184:187], v204, s[92:93]
	s_and_b64 vcc, exec, s[2:3]
	s_cbranch_vccz .Lpg_w2_7
	s_waitcnt vmcnt(6)
	s_branch .Lpg_wd_7

; __device__ __forceinline__ unsigned cvt_pk_bf16(float lo, float hi) { unsigned r; asm volatile("v_cvt_pk_bf16_f32 %0, %1, %2" : "=v"(r) : "v"(lo), "v"(hi)); return r; }
; __device__ __forceinline__ float bf_lo(unsigned w) { return __uint_as_float(w << 16); }
; __device__ __forceinline__ float bf_hi(unsigned w) { return __uint_as_float(w & 0xffff0000u); }
;     __device__ __forceinline__ void operator()(const f32x4 (&acc)[2][2][4][2], const Unit& u, int wr, int wc, int fr, int fq) const {
;     ...
;             for (int n = 0; n < 2; ++n) { c1[n] = *(const f32x4*)(C1 + col + 4 * n); c2[n] = *(const f32x4*)(C2 + col + 4 * n); lg[n] = *(const f32x4*)(LG + col + 4 * n); lb[n] = *(const f32x4*)(LB + col + 4 * n); }
; #pragma unroll
;             for (int ai = 0; ai < 2; ++ai)
; #pragma unroll
;                 for (int m = 0; m < 4; ++m) { const int row = row0 + ai * HALF + m * 16; const size_t o2 = (size_t)row * ldc + col;
;                     const float s1 = ST[2 * row], s2 = ST[2 * row + 1], mu = s1 * (1.f / 2048.f), rstd = __builtin_amdgcn_rsqf(fmaxf(s2 * (1.f / 2048.f) - mu * mu, 0.f) + 1e-5f);
;                     const u32x4 zw = *(const u32x4*)(Zb + o2), pw = *(const u32x4*)(PE + o2); u32x4 xw;
; #pragma unroll
;                     for (int n = 0; n < 2; ++n) { const unsigned za = n ? zw.z : zw.x, zb2 = n ? zw.w : zw.y, pa = n ? pw.z : pw.x, pb = n ? pw.w : pw.y;
;                         const float zv[4] = {bf_lo(za), bf_hi(za), bf_lo(zb2), bf_hi(zb2)}, pv[4] = {bf_lo(pa), bf_hi(pa), bf_lo(pb), bf_hi(pb)}; const f32x4 a = acc[ai][bj][m][n]; f32x4 o;
; #pragma unroll
;                         for (int e = 0; e < 4; ++e) { const float sv = rstd * (a[e] - mu * c1[n][e]) + c2[n][e]; const float xl = (zv[e] - mu) * rstd * lg[n][e] + lb[n][e]; o[e] = xl + pv[e] * __builtin_amdgcn_rcpf(1.f + __expf(-sv)); }
;                         *(f32x4*)(OUTF + o2 + 4 * n) = o; if (n == 0) { xw.x = cvt_pk_bf16(o[0], o[1]); xw.y = cvt_pk_bf16(o[2], o[3]); } else { xw.z = cvt_pk_bf16(o[0], o[1]); xw.w = cvt_pk_bf16(o[2], o[3]); } }
;                     if (XB) *(u32x4*)(XB + o2) = xw; }
.Lpg_wd_7:
	v_pk_mul_f32 v[210:211], v[162:163], s[0:1] op_sel_hi:[1,0]
	v_lshlrev_b32_e32 v224, 1, v226
	v_fma_f32 v212, -v210, v210, v211
	v_max_f32_e32 v212, 0, v212
	v_add_f32_e32 v212, 0x3727c5ac, v212
	v_rsq_f32_e32 v212, v212
	v_fma_f32 v68, -v88, v210, v68
	v_fma_f32 v69, -v89, v210, v69
	v_fma_f32 v70, -v90, v210, v70
	v_fma_f32 v71, -v91, v210, v71
	v_fma_f32 v68, v68, v212, v96
	v_fma_f32 v69, v69, v212, v97
	v_fma_f32 v70, v70, v212, v98
	v_fma_f32 v71, v71, v212, v99
	v_mul_f32_e32 v68, 0xbfb8aa3b, v68
	v_mul_f32_e32 v69, 0xbfb8aa3b, v69
	v_mul_f32_e32 v70, 0xbfb8aa3b, v70
	v_mul_f32_e32 v71, 0xbfb8aa3b, v71
	v_exp_f32_e32 v68, v68
	v_exp_f32_e32 v69, v69
	v_exp_f32_e32 v70, v70
	v_exp_f32_e32 v71, v71
	v_add_f32_e32 v68, 1.0, v68
	v_add_f32_e32 v69, 1.0, v69
	v_add_f32_e32 v70, 1.0, v70
	v_add_f32_e32 v71, 1.0, v71
	v_rcp_f32_e32 v68, v68
	v_rcp_f32_e32 v69, v69
	v_rcp_f32_e32 v70, v70
	v_rcp_f32_e32 v71, v71
	v_lshlrev_b32_e32 v202, 16, v188
	v_and_b32_e32 v203, 0xffff0000, v188
	v_lshlrev_b32_e32 v200, 16, v192
	v_and_b32_e32 v201, 0xffff0000, v192
	v_pk_add_f32 v[202:203], v[202:203], v[210:211] op_sel_hi:[1,0] neg_lo:[0,1] neg_hi:[0,1]
	v_pk_mul_f32 v[202:203], v[212:213], v[202:203] op_sel_hi:[0,1]
	v_pk_fma_f32 v[202:203], v[104:105], v[202:203], v[116:117]
	v_pk_fma_f32 v[68:69], v[68:69], v[200:201], v[202:203]
	v_lshlrev_b32_e32 v202, 16, v189
	v_and_b32_e32 v203, 0xffff0000, v189
	v_lshlrev_b32_e32 v200, 16, v193
	v_and_b32_e32 v201, 0xffff0000, v193
	v_pk_add_f32 v[202:203], v[202:203], v[210:211] op_sel_hi:[1,0] neg_lo:[0,1] neg_hi:[0,1]
	v_pk_mul_f32 v[202:203], v[212:213], v[202:203] op_sel_hi:[0,1]
	v_pk_fma_f32 v[202:203], v[106:107], v[202:203], v[118:119]
	v_pk_fma_f32 v[70:71], v[70:71], v[200:201], v[202:203]
	global_store_dwordx4 v224, v[68:71], s[8:9]
	v_cvt_pk_bf16_f32 v196, v68, v69
	v_cvt_pk_bf16_f32 v197, v70, v71
	v_fma_f32 v64, -v92, v210, v64
	v_fma_f32 v65, -v93, v210, v65
	v_fma_f32 v66, -v94, v210, v66
	v_fma_f32 v67, -v95, v210, v67
	v_fma_f32 v64, v64, v212, v100
	v_fma_f32 v65, v65, v212, v101
	v_fma_f32 v66, v66, v212, v102
	v_fma_f32 v67, v67, v212, v103
	v_mul_f32_e32 v64, 0xbfb8aa3b, v64
	v_mul_f32_e32 v65, 0xbfb8aa3b, v65
	v_mul_f32_e32 v66, 0xbfb8aa3b, v66
	v_mul_f32_e32 v67, 0xbfb8aa3b, v67
	v_exp_f32_e32 v64, v64
	v_exp_f32_e32 v65, v65
	v_exp_f32_e32 v66, v66
	v_exp_f32_e32 v67, v67
	v_add_f32_e32 v64, 1.0, v64
	v_add_f32_e32 v65, 1.0, v65
	v_add_f32_e32 v66, 1.0, v66
	v_add_f32_e32 v67, 1.0, v67
	v_rcp_f32_e32 v64, v64
	v_rcp_f32_e32 v65, v65
	v_rcp_f32_e32 v66, v66
	v_rcp_f32_e32 v67, v67
	v_lshlrev_b32_e32 v202, 16, v190
	v_and_b32_e32 v203, 0xffff0000, v190
	v_lshlrev_b32_e32 v200, 16, v194
	v_and_b32_e32 v201, 0xffff0000, v194
	v_pk_add_f32 v[202:203], v[202:203], v[210:211] op_sel_hi:[1,0] neg_lo:[0,1] neg_hi:[0,1]
	v_pk_mul_f32 v[202:203], v[212:213], v[202:203] op_sel_hi:[0,1]
	v_pk_fma_f32 v[202:203], v[108:109], v[202:203], v[124:125]
	v_pk_fma_f32 v[64:65], v[64:65], v[200:201], v[202:203]
	v_lshlrev_b32_e32 v202, 16, v191
	v_and_b32_e32 v203, 0xffff0000, v191
	v_lshlrev_b32_e32 v200, 16, v195
	v_and_b32_e32 v201, 0xffff0000, v195
	v_pk_add_f32 v[202:203], v[202:203], v[210:211] op_sel_hi:[1,0] neg_lo:[0,1] neg_hi:[0,1]
	v_pk_mul_f32 v[202:203], v[212:213], v[202:203] op_sel_hi:[0,1]
	v_pk_fma_f32 v[202:203], v[110:111], v[202:203], v[126:127]
	v_pk_fma_f32 v[66:67], v[66:67], v[200:201], v[202:203]
	global_store_dwordx4 v224, v[64:67], s[8:9] offset:16
	v_cvt_pk_bf16_f32 v198, v64, v65
	v_cvt_pk_bf16_f32 v199, v66, v67
	global_load_dwordx4 v[88:91], v225, s[96:97] offset:512
	global_load_dwordx4 v[96:99], v225, s[4:5] offset:512
	global_load_dwordx4 v[104:107], v225, s[56:57] offset:512
	global_load_dwordx4 v[116:119], v225, s[58:59] offset:512
	global_load_dwordx4 v[92:95], v225, s[96:97] offset:528
	global_load_dwordx4 v[100:103], v225, s[4:5] offset:528
	global_load_dwordx4 v[108:111], v225, s[56:57] offset:528
	global_load_dwordx4 v[124:127], v225, s[58:59] offset:528
	s_and_b64 vcc, exec, s[2:3]
	s_cbranch_vccz .Lpg_nx_7
	global_store_dwordx4 v226, v[196:199], s[90:91]
; __device__ __forceinline__ unsigned cvt_pk_bf16(float lo, float hi) { unsigned r; asm volatile("v_cvt_pk_bf16_f32 %0, %1, %2" : "=v"(r) : "v"(lo), "v"(hi)); return r; }
; __device__ __forceinline__ float bf_lo(unsigned w) { return __uint_as_float(w << 16); }
; __device__ __forceinline__ float bf_hi(unsigned w) { return __uint_as_float(w & 0xffff0000u); }
;     __device__ __forceinline__ void operator()(const f32x4 (&acc)[2][2][4][2], const Unit& u, int wr, int wc, int fr, int fq) const {
;     ...
;                 for (int m = 0; m < 4; ++m) { const int row = row0 + ai * HALF + m * 16; const size_t o2 = (size_t)row * ldc + col;
;                     const float s1 = ST[2 * row], s2 = ST[2 * row + 1], mu = s1 * (1.f / 2048.f), rstd = __builtin_amdgcn_rsqf(fmaxf(s2 * (1.f / 2048.f) - mu * mu, 0.f) + 1e-5f);
;                     const u32x4 zw = *(const u32x4*)(Zb + o2), pw = *(const u32x4*)(PE + o2); u32x4 xw;
; #pragma unroll
;                     for (int n = 0; n < 2; ++n) { const unsigned za = n ? zw.z : zw.x, zb2 = n ? zw.w : zw.y, pa = n ? pw.z : pw.x, pb = n ? pw.w : pw.y;
;                         const float zv[4] = {bf_lo(za), bf_hi(za), bf_lo(zb2), bf_hi(zb2)}, pv[4] = {bf_lo(pa), bf_hi(pa), bf_lo(pb), bf_hi(pb)}; const f32x4 a = acc[ai][bj][m][n]; f32x4 o;
; #pragma unroll
;                         for (int e = 0; e < 4; ++e) { const float sv = rstd * (a[e] - mu * c1[n][e]) + c2[n][e]; const float xl = (zv[e] - mu) * rstd * lg[n][e] + lb[n][e]; o[e] = xl + pv[e] * __builtin_amdgcn_rcpf(1.f + __expf(-sv)); }
;                         *(f32x4*)(OUTF + o2 + 4 * n) = o; if (n == 0) { xw.x = cvt_pk_bf16(o[0], o[1]); xw.y = cvt_pk_bf16(o[2], o[3]); } else { xw.z = cvt_pk_bf16(o[0], o[1]); xw.w = cvt_pk_bf16(o[2], o[3]); } }
;                     if (XB) *(u32x4*)(XB + o2) = xw; }
.Lpg_nx_7:
	v_mov_b32_e32 v226, v204
	v_add_u32_e32 v204, 0x10000, v204
	global_load_dwordx2 v[162:163], v209, s[94:95] offset:128
	global_load_dwordx4 v[188:191], v204, s[82:83]
	global_load_dwordx4 v[192:195], v204, s[92:93]
	s_and_b64 vcc, exec, s[2:3]
	s_cbranch_vccz .Lpg_w2_8
	s_waitcnt vmcnt(4)
	s_branch .Lpg_wd_8
.Lpg_w2_8:
	s_waitcnt vmcnt(3)
.Lpg_wd_8:
	v_pk_mul_f32 v[210:211], v[160:161], s[0:1] op_sel_hi:[1,0]
	v_lshlrev_b32_e32 v224, 1, v226
	v_fma_f32 v212, -v210, v210, v211
	v_max_f32_e32 v212, 0, v212
	v_add_f32_e32 v212, 0x3727c5ac, v212
	v_rsq_f32_e32 v212, v212
	v_fma_f32 v60, -v88, v210, v60
	v_fma_f32 v61, -v89, v210, v61
	v_fma_f32 v62, -v90, v210, v62
	v_fma_f32 v63, -v91, v210, v63
	v_fma_f32 v60, v60, v212, v96
	v_fma_f32 v61, v61, v212, v97
	v_fma_f32 v62, v62, v212, v98
	v_fma_f32 v63, v63, v212, v99
	v_mul_f32_e32 v60, 0xbfb8aa3b, v60
	v_mul_f32_e32 v61, 0xbfb8aa3b, v61
	v_mul_f32_e32 v62, 0xbfb8aa3b, v62
	v_mul_f32_e32 v63, 0xbfb8aa3b, v63
	v_exp_f32_e32 v60, v60
	v_exp_f32_e32 v61, v61
	v_exp_f32_e32 v62, v62
	v_exp_f32_e32 v63, v63
	v_add_f32_e32 v60, 1.0, v60
	v_add_f32_e32 v61, 1.0, v61
	v_add_f32_e32 v62, 1.0, v62
	v_add_f32_e32 v63, 1.0, v63
	v_rcp_f32_e32 v60, v60
	v_rcp_f32_e32 v61, v61
	v_rcp_f32_e32 v62, v62
	v_rcp_f32_e32 v63, v63
	v_lshlrev_b32_e32 v202, 16, v164
	v_and_b32_e32 v203, 0xffff0000, v164
	v_lshlrev_b32_e32 v200, 16, v184
	v_and_b32_e32 v201, 0xffff0000, v184
	v_pk_add_f32 v[202:203], v[202:203], v[210:211] op_sel_hi:[1,0] neg_lo:[0,1] neg_hi:[0,1]
	v_pk_mul_f32 v[202:203], v[212:213], v[202:203] op_sel_hi:[0,1]
	v_pk_fma_f32 v[202:203], v[104:105], v[202:203], v[116:117]
	v_pk_fma_f32 v[60:61], v[60:61], v[200:201], v[202:203]
	v_lshlrev_b32_e32 v202, 16, v165
	v_and_b32_e32 v203, 0xffff0000, v165
	v_lshlrev_b32_e32 v200, 16, v185
	v_and_b32_e32 v201, 0xffff0000, v185
	v_pk_add_f32 v[202:203], v[202:203], v[210:211] op_sel_hi:[1,0] neg_lo:[0,1] neg_hi:[0,1]
	v_pk_mul_f32 v[202:203], v[212:213], v[202:203] op_sel_hi:[0,1]
	v_pk_fma_f32 v[202:203], v[106:107], v[202:203], v[118:119]
	v_pk_fma_f32 v[62:63], v[62:63], v[200:201], v[202:203]
	global_store_dwordx4 v224, v[60:63], s[8:9]
	v_cvt_pk_bf16_f32 v196, v60, v61
	v_cvt_pk_bf16_f32 v197, v62, v63
	v_fma_f32 v56, -v92, v210, v56
	v_fma_f32 v57, -v93, v210, v57
	v_fma_f32 v58, -v94, v210, v58
	v_fma_f32 v59, -v95, v210, v59
	v_fma_f32 v56, v56, v212, v100
	v_fma_f32 v57, v57, v212, v101
	v_fma_f32 v58, v58, v212, v102
	v_fma_f32 v59, v59, v212, v103
	v_mul_f32_e32 v56, 0xbfb8aa3b, v56
	v_mul_f32_e32 v57, 0xbfb8aa3b, v57
	v_mul_f32_e32 v58, 0xbfb8aa3b, v58
	v_mul_f32_e32 v59, 0xbfb8aa3b, v59
	v_exp_f32_e32 v56, v56
	v_exp_f32_e32 v57, v57
	v_exp_f32_e32 v58, v58
	v_exp_f32_e32 v59, v59
	v_add_f32_e32 v56, 1.0, v56
	v_add_f32_e32 v57, 1.0, v57
	v_add_f32_e32 v58, 1.0, v58
	v_add_f32_e32 v59, 1.0, v59
	v_rcp_f32_e32 v56, v56
	v_rcp_f32_e32 v57, v57
	v_rcp_f32_e32 v58, v58
	v_rcp_f32_e32 v59, v59
	v_lshlrev_b32_e32 v202, 16, v166
	v_and_b32_e32 v203, 0xffff0000, v166
	v_lshlrev_b32_e32 v200, 16, v186
	v_and_b32_e32 v201, 0xffff0000, v186
	v_pk_add_f32 v[202:203], v[202:203], v[210:211] op_sel_hi:[1,0] neg_lo:[0,1] neg_hi:[0,1]
	v_pk_mul_f32 v[202:203], v[212:213], v[202:203] op_sel_hi:[0,1]
	v_pk_fma_f32 v[202:203], v[108:109], v[202:203], v[124:125]
	v_pk_fma_f32 v[56:57], v[56:57], v[200:201], v[202:203]
	v_lshlrev_b32_e32 v202, 16, v167
	v_and_b32_e32 v203, 0xffff0000, v167
	v_lshlrev_b32_e32 v200, 16, v187
	v_and_b32_e32 v201, 0xffff0000, v187
	v_pk_add_f32 v[202:203], v[202:203], v[210:211] op_sel_hi:[1,0] neg_lo:[0,1] neg_hi:[0,1]
	v_pk_mul_f32 v[202:203], v[212:213], v[202:203] op_sel_hi:[0,1]
	v_pk_fma_f32 v[202:203], v[110:111], v[202:203], v[126:127]
	v_pk_fma_f32 v[58:59], v[58:59], v[200:201], v[202:203]
	global_store_dwordx4 v224, v[56:59], s[8:9] offset:16
	v_cvt_pk_bf16_f32 v198, v56, v57
	v_cvt_pk_bf16_f32 v199, v58, v59
	s_and_b64 vcc, exec, s[2:3]
	s_cbranch_vccz .Lpg_nx_8
	global_store_dwordx4 v226, v[196:199], s[90:91]

; __device__ __forceinline__ unsigned cvt_pk_bf16(float lo, float hi) { unsigned r; asm volatile("v_cvt_pk_bf16_f32 %0, %1, %2" : "=v"(r) : "v"(lo), "v"(hi)); return r; }
; __device__ __forceinline__ float bf_lo(unsigned w) { return __uint_as_float(w << 16); }
; __device__ __forceinline__ float bf_hi(unsigned w) { return __uint_as_float(w & 0xffff0000u); }
;     __device__ __forceinline__ void operator()(const f32x4 (&acc)[2][2][4][2], const Unit& u, int wr, int wc, int fr, int fq) const {
;     ...
;                 for (int m = 0; m < 4; ++m) { const int row = row0 + ai * HALF + m * 16; const size_t o2 = (size_t)row * ldc + col;
;                     const float s1 = ST[2 * row], s2 = ST[2 * row + 1], mu = s1 * (1.f / 2048.f), rstd = __builtin_amdgcn_rsqf(fmaxf(s2 * (1.f / 2048.f) - mu * mu, 0.f) + 1e-5f);
;                     const u32x4 zw = *(const u32x4*)(Zb + o2), pw = *(const u32x4*)(PE + o2); u32x4 xw;
; #pragma unroll
;                     for (int n = 0; n < 2; ++n) { const unsigned za = n ? zw.z : zw.x, zb2 = n ? zw.w : zw.y, pa = n ? pw.z : pw.x, pb = n ? pw.w : pw.y;
;                         const float zv[4] = {bf_lo(za), bf_hi(za), bf_lo(zb2), bf_hi(zb2)}, pv[4] = {bf_lo(pa), bf_hi(pa), bf_lo(pb), bf_hi(pb)}; const f32x4 a = acc[ai][bj][m][n]; f32x4 o;
; #pragma unroll
;                         for (int e = 0; e < 4; ++e) { const float sv = rstd * (a[e] - mu * c1[n][e]) + c2[n][e]; const float xl = (zv[e] - mu) * rstd * lg[n][e] + lb[n][e]; o[e] = xl + pv[e] * __builtin_amdgcn_rcpf(1.f + __expf(-sv)); }
;                         *(f32x4*)(OUTF + o2 + 4 * n) = o; if (n == 0) { xw.x = cvt_pk_bf16(o[0], o[1]); xw.y = cvt_pk_bf16(o[2], o[3]); } else { xw.z = cvt_pk_bf16(o[0], o[1]); xw.w = cvt_pk_bf16(o[2], o[3]); } }
;                     if (XB) *(u32x4*)(XB + o2) = xw; }
.Lpg_wd_9:
	v_pk_mul_f32 v[210:211], v[162:163], s[0:1] op_sel_hi:[1,0]
	v_lshlrev_b32_e32 v224, 1, v226
	v_fma_f32 v212, -v210, v210, v211
	v_max_f32_e32 v212, 0, v212
	v_add_f32_e32 v212, 0x3727c5ac, v212
	v_rsq_f32_e32 v212, v212
	v_fma_f32 v52, -v88, v210, v52
	v_fma_f32 v53, -v89, v210, v53
	v_fma_f32 v54, -v90, v210, v54
	v_fma_f32 v55, -v91, v210, v55
	v_fma_f32 v52, v52, v212, v96
	v_fma_f32 v53, v53, v212, v97
	v_fma_f32 v54, v54, v212, v98
	v_fma_f32 v55, v55, v212, v99
	v_mul_f32_e32 v52, 0xbfb8aa3b, v52
	v_mul_f32_e32 v53, 0xbfb8aa3b, v53
	v_mul_f32_e32 v54, 0xbfb8aa3b, v54
	v_mul_f32_e32 v55, 0xbfb8aa3b, v55
	v_exp_f32_e32 v52, v52
	v_exp_f32_e32 v53, v53
	v_exp_f32_e32 v54, v54
	v_exp_f32_e32 v55, v55
	v_add_f32_e32 v52, 1.0, v52
	v_add_f32_e32 v53, 1.0, v53
	v_add_f32_e32 v54, 1.0, v54
	v_add_f32_e32 v55, 1.0, v55
	v_rcp_f32_e32 v52, v52
	v_rcp_f32_e32 v53, v53
	v_rcp_f32_e32 v54, v54
	v_rcp_f32_e32 v55, v55
	v_lshlrev_b32_e32 v202, 16, v188
	v_and_b32_e32 v203, 0xffff0000, v188
	v_lshlrev_b32_e32 v200, 16, v192
	v_and_b32_e32 v201, 0xffff0000, v192
	v_pk_add_f32 v[202:203], v[202:203], v[210:211] op_sel_hi:[1,0] neg_lo:[0,1] neg_hi:[0,1]
	v_pk_mul_f32 v[202:203], v[212:213], v[202:203] op_sel_hi:[0,1]
	v_pk_fma_f32 v[202:203], v[104:105], v[202:203], v[116:117]
	v_pk_fma_f32 v[52:53], v[52:53], v[200:201], v[202:203]
	v_lshlrev_b32_e32 v202, 16, v189
	v_and_b32_e32 v203, 0xffff0000, v189
	v_lshlrev_b32_e32 v200, 16, v193
	v_and_b32_e32 v201, 0xffff0000, v193
	v_pk_add_f32 v[202:203], v[202:203], v[210:211] op_sel_hi:[1,0] neg_lo:[0,1] neg_hi:[0,1]
	v_pk_mul_f32 v[202:203], v[212:213], v[202:203] op_sel_hi:[0,1]
	v_pk_fma_f32 v[202:203], v[106:107], v[202:203], v[118:119]
	v_pk_fma_f32 v[54:55], v[54:55], v[200:201], v[202:203]
	global_store_dwordx4 v224, v[52:55], s[8:9]
	v_cvt_pk_bf16_f32 v196, v52, v53
	v_cvt_pk_bf16_f32 v197, v54, v55
	v_fma_f32 v48, -v92, v210, v48
	v_fma_f32 v49, -v93, v210, v49
	v_fma_f32 v50, -v94, v210, v50
	v_fma_f32 v51, -v95, v210, v51
	v_fma_f32 v48, v48, v212, v100
	v_fma_f32 v49, v49, v212, v101
	v_fma_f32 v50, v50, v212, v102
	v_fma_f32 v51, v51, v212, v103
	v_mul_f32_e32 v48, 0xbfb8aa3b, v48
	v_mul_f32_e32 v49, 0xbfb8aa3b, v49
	v_mul_f32_e32 v50, 0xbfb8aa3b, v50
	v_mul_f32_e32 v51, 0xbfb8aa3b, v51
	v_exp_f32_e32 v48, v48
	v_exp_f32_e32 v49, v49
	v_exp_f32_e32 v50, v50
	v_exp_f32_e32 v51, v51
	v_add_f32_e32 v48, 1.0, v48
	v_add_f32_e32 v49, 1.0, v49
	v_add_f32_e32 v50, 1.0, v50
	v_add_f32_e32 v51, 1.0, v51
	v_rcp_f32_e32 v48, v48
	v_rcp_f32_e32 v49, v49
	v_rcp_f32_e32 v50, v50
	v_rcp_f32_e32 v51, v51
	v_lshlrev_b32_e32 v202, 16, v190
	v_and_b32_e32 v203, 0xffff0000, v190
	v_lshlrev_b32_e32 v200, 16, v194
	v_and_b32_e32 v201, 0xffff0000, v194
	v_pk_add_f32 v[202:203], v[202:203], v[210:211] op_sel_hi:[1,0] neg_lo:[0,1] neg_hi:[0,1]
	v_pk_mul_f32 v[202:203], v[212:213], v[202:203] op_sel_hi:[0,1]
	v_pk_fma_f32 v[202:203], v[108:109], v[202:203], v[124:125]
	v_pk_fma_f32 v[48:49], v[48:49], v[200:201], v[202:203]
	v_lshlrev_b32_e32 v202, 16, v191
	v_and_b32_e32 v203, 0xffff0000, v191
	v_lshlrev_b32_e32 v200, 16, v195
	v_and_b32_e32 v201, 0xffff0000, v195
	v_pk_add_f32 v[202:203], v[202:203], v[210:211] op_sel_hi:[1,0] neg_lo:[0,1] neg_hi:[0,1]
	v_pk_mul_f32 v[202:203], v[212:213], v[202:203] op_sel_hi:[0,1]
	v_pk_fma_f32 v[202:203], v[110:111], v[202:203], v[126:127]
	v_pk_fma_f32 v[50:51], v[50:51], v[200:201], v[202:203]
	global_store_dwordx4 v224, v[48:51], s[8:9] offset:16
	v_cvt_pk_bf16_f32 v198, v48, v49
	v_cvt_pk_bf16_f32 v199, v50, v51
	s_and_b64 vcc, exec, s[2:3]
	s_cbranch_vccz .Lpg_nx_9
	global_store_dwordx4 v226, v[196:199], s[90:91]

; __device__ __forceinline__ unsigned cvt_pk_bf16(float lo, float hi) { unsigned r; asm volatile("v_cvt_pk_bf16_f32 %0, %1, %2" : "=v"(r) : "v"(lo), "v"(hi)); return r; }
; __device__ __forceinline__ float bf_lo(unsigned w) { return __uint_as_float(w << 16); }
; __device__ __forceinline__ float bf_hi(unsigned w) { return __uint_as_float(w & 0xffff0000u); }
;     __device__ __forceinline__ void operator()(const f32x4 (&acc)[2][2][4][2], const Unit& u, int wr, int wc, int fr, int fq) const {
;     ...
;                 for (int m = 0; m < 4; ++m) { const int row = row0 + ai * HALF + m * 16; const size_t o2 = (size_t)row * ldc + col;
;                     const float s1 = ST[2 * row], s2 = ST[2 * row + 1], mu = s1 * (1.f / 2048.f), rstd = __builtin_amdgcn_rsqf(fmaxf(s2 * (1.f / 2048.f) - mu * mu, 0.f) + 1e-5f);
;                     const u32x4 zw = *(const u32x4*)(Zb + o2), pw = *(const u32x4*)(PE + o2); u32x4 xw;
; #pragma unroll
;                     for (int n = 0; n < 2; ++n) { const unsigned za = n ? zw.z : zw.x, zb2 = n ? zw.w : zw.y, pa = n ? pw.z : pw.x, pb = n ? pw.w : pw.y;
;                         const float zv[4] = {bf_lo(za), bf_hi(za), bf_lo(zb2), bf_hi(zb2)}, pv[4] = {bf_lo(pa), bf_hi(pa), bf_lo(pb), bf_hi(pb)}; const f32x4 a = acc[ai][bj][m][n]; f32x4 o;
; #pragma unroll
;                         for (int e = 0; e < 4; ++e) { const float sv = rstd * (a[e] - mu * c1[n][e]) + c2[n][e]; const float xl = (zv[e] - mu) * rstd * lg[n][e] + lb[n][e]; o[e] = xl + pv[e] * __builtin_amdgcn_rcpf(1.f + __expf(-sv)); }
;                         *(f32x4*)(OUTF + o2 + 4 * n) = o; if (n == 0) { xw.x = cvt_pk_bf16(o[0], o[1]); xw.y = cvt_pk_bf16(o[2], o[3]); } else { xw.z = cvt_pk_bf16(o[0], o[1]); xw.w = cvt_pk_bf16(o[2], o[3]); } }
;                     if (XB) *(u32x4*)(XB + o2) = xw; }
.Lpg_wd_10:
	v_pk_mul_f32 v[210:211], v[160:161], s[0:1] op_sel_hi:[1,0]
	v_lshlrev_b32_e32 v224, 1, v226
	v_fma_f32 v212, -v210, v210, v211
	v_max_f32_e32 v212, 0, v212
	v_add_f32_e32 v212, 0x3727c5ac, v212
	v_rsq_f32_e32 v212, v212
	v_fma_f32 v44, -v88, v210, v44
	v_fma_f32 v45, -v89, v210, v45
	v_fma_f32 v46, -v90, v210, v46
	v_fma_f32 v47, -v91, v210, v47
	v_fma_f32 v44, v44, v212, v96
	v_fma_f32 v45, v45, v212, v97
	v_fma_f32 v46, v46, v212, v98
	v_fma_f32 v47, v47, v212, v99
	v_mul_f32_e32 v44, 0xbfb8aa3b, v44
	v_mul_f32_e32 v45, 0xbfb8aa3b, v45
	v_mul_f32_e32 v46, 0xbfb8aa3b, v46
	v_mul_f32_e32 v47, 0xbfb8aa3b, v47
	v_exp_f32_e32 v44, v44
	v_exp_f32_e32 v45, v45
	v_exp_f32_e32 v46, v46
	v_exp_f32_e32 v47, v47
	v_add_f32_e32 v44, 1.0, v44
	v_add_f32_e32 v45, 1.0, v45
	v_add_f32_e32 v46, 1.0, v46
	v_add_f32_e32 v47, 1.0, v47
	v_rcp_f32_e32 v44, v44
	v_rcp_f32_e32 v45, v45
	v_rcp_f32_e32 v46, v46
	v_rcp_f32_e32 v47, v47
	v_lshlrev_b32_e32 v202, 16, v164
	v_and_b32_e32 v203, 0xffff0000, v164
	v_lshlrev_b32_e32 v200, 16, v184
	v_and_b32_e32 v201, 0xffff0000, v184
	v_pk_add_f32 v[202:203], v[202:203], v[210:211] op_sel_hi:[1,0] neg_lo:[0,1] neg_hi:[0,1]
	v_pk_mul_f32 v[202:203], v[212:213], v[202:203] op_sel_hi:[0,1]
	v_pk_fma_f32 v[202:203], v[104:105], v[202:203], v[116:117]
	v_pk_fma_f32 v[44:45], v[44:45], v[200:201], v[202:203]
	v_lshlrev_b32_e32 v202, 16, v165
	v_and_b32_e32 v203, 0xffff0000, v165
	v_lshlrev_b32_e32 v200, 16, v185
	v_and_b32_e32 v201, 0xffff0000, v185
	v_pk_add_f32 v[202:203], v[202:203], v[210:211] op_sel_hi:[1,0] neg_lo:[0,1] neg_hi:[0,1]
	v_pk_mul_f32 v[202:203], v[212:213], v[202:203] op_sel_hi:[0,1]
	v_pk_fma_f32 v[202:203], v[106:107], v[202:203], v[118:119]
	v_pk_fma_f32 v[46:47], v[46:47], v[200:201], v[202:203]
	global_store_dwordx4 v224, v[44:47], s[8:9]
	v_cvt_pk_bf16_f32 v196, v44, v45
	v_cvt_pk_bf16_f32 v197, v46, v47
	v_fma_f32 v40, -v92, v210, v40
	v_fma_f32 v41, -v93, v210, v41
	v_fma_f32 v42, -v94, v210, v42
	v_fma_f32 v43, -v95, v210, v43
	v_fma_f32 v40, v40, v212, v100
	v_fma_f32 v41, v41, v212, v101
	v_fma_f32 v42, v42, v212, v102
	v_fma_f32 v43, v43, v212, v103
	v_mul_f32_e32 v40, 0xbfb8aa3b, v40
	v_mul_f32_e32 v41, 0xbfb8aa3b, v41
	v_mul_f32_e32 v42, 0xbfb8aa3b, v42
	v_mul_f32_e32 v43, 0xbfb8aa3b, v43
	v_exp_f32_e32 v40, v40
	v_exp_f32_e32 v41, v41
	v_exp_f32_e32 v42, v42
	v_exp_f32_e32 v43, v43
	v_add_f32_e32 v40, 1.0, v40
	v_add_f32_e32 v41, 1.0, v41
	v_add_f32_e32 v42, 1.0, v42
	v_add_f32_e32 v43, 1.0, v43
	v_rcp_f32_e32 v40, v40
	v_rcp_f32_e32 v41, v41
	v_rcp_f32_e32 v42, v42
	v_rcp_f32_e32 v43, v43
	v_lshlrev_b32_e32 v202, 16, v166
	v_and_b32_e32 v203, 0xffff0000, v166
	v_lshlrev_b32_e32 v200, 16, v186
	v_and_b32_e32 v201, 0xffff0000, v186
	v_pk_add_f32 v[202:203], v[202:203], v[210:211] op_sel_hi:[1,0] neg_lo:[0,1] neg_hi:[0,1]
	v_pk_mul_f32 v[202:203], v[212:213], v[202:203] op_sel_hi:[0,1]
	v_pk_fma_f32 v[202:203], v[108:109], v[202:203], v[124:125]
	v_pk_fma_f32 v[40:41], v[40:41], v[200:201], v[202:203]
	v_lshlrev_b32_e32 v202, 16, v167
	v_and_b32_e32 v203, 0xffff0000, v167
	v_lshlrev_b32_e32 v200, 16, v187
	v_and_b32_e32 v201, 0xffff0000, v187
	v_pk_add_f32 v[202:203], v[202:203], v[210:211] op_sel_hi:[1,0] neg_lo:[0,1] neg_hi:[0,1]
	v_pk_mul_f32 v[202:203], v[212:213], v[202:203] op_sel_hi:[0,1]
	v_pk_fma_f32 v[202:203], v[110:111], v[202:203], v[126:127]
	v_pk_fma_f32 v[42:43], v[42:43], v[200:201], v[202:203]
	global_store_dwordx4 v224, v[40:43], s[8:9] offset:16
	v_cvt_pk_bf16_f32 v198, v40, v41
	v_cvt_pk_bf16_f32 v199, v42, v43
	s_and_b64 vcc, exec, s[2:3]
	s_cbranch_vccz .Lpg_nx_10
	global_store_dwordx4 v226, v[196:199], s[90:91]

; __device__ __forceinline__ unsigned cvt_pk_bf16(float lo, float hi) { unsigned r; asm volatile("v_cvt_pk_bf16_f32 %0, %1, %2" : "=v"(r) : "v"(lo), "v"(hi)); return r; }
; __device__ __forceinline__ float bf_lo(unsigned w) { return __uint_as_float(w << 16); }
; __device__ __forceinline__ float bf_hi(unsigned w) { return __uint_as_float(w & 0xffff0000u); }
;     __device__ __forceinline__ void operator()(const f32x4 (&acc)[2][2][4][2], const Unit& u, int wr, int wc, int fr, int fq) const {
;     ...
;                 for (int m = 0; m < 4; ++m) { const int row = row0 + ai * HALF + m * 16; const size_t o2 = (size_t)row * ldc + col;
;                     const float s1 = ST[2 * row], s2 = ST[2 * row + 1], mu = s1 * (1.f / 2048.f), rstd = __builtin_amdgcn_rsqf(fmaxf(s2 * (1.f / 2048.f) - mu * mu, 0.f) + 1e-5f);
;                     const u32x4 zw = *(const u32x4*)(Zb + o2), pw = *(const u32x4*)(PE + o2); u32x4 xw;
; #pragma unroll
;                     for (int n = 0; n < 2; ++n) { const unsigned za = n ? zw.z : zw.x, zb2 = n ? zw.w : zw.y, pa = n ? pw.z : pw.x, pb = n ? pw.w : pw.y;
;                         const float zv[4] = {bf_lo(za), bf_hi(za), bf_lo(zb2), bf_hi(zb2)}, pv[4] = {bf_lo(pa), bf_hi(pa), bf_lo(pb), bf_hi(pb)}; const f32x4 a = acc[ai][bj][m][n]; f32x4 o;
; #pragma unroll
;                         for (int e = 0; e < 4; ++e) { const float sv = rstd * (a[e] - mu * c1[n][e]) + c2[n][e]; const float xl = (zv[e] - mu) * rstd * lg[n][e] + lb[n][e]; o[e] = xl + pv[e] * __builtin_amdgcn_rcpf(1.f + __expf(-sv)); }
;                         *(f32x4*)(OUTF + o2 + 4 * n) = o; if (n == 0) { xw.x = cvt_pk_bf16(o[0], o[1]); xw.y = cvt_pk_bf16(o[2], o[3]); } else { xw.z = cvt_pk_bf16(o[0], o[1]); xw.w = cvt_pk_bf16(o[2], o[3]); } }
;                     if (XB) *(u32x4*)(XB + o2) = xw; }
.Lpg_wd_11:
	v_pk_mul_f32 v[210:211], v[162:163], s[0:1] op_sel_hi:[1,0]
	v_lshlrev_b32_e32 v224, 1, v226
	v_fma_f32 v212, -v210, v210, v211
	v_max_f32_e32 v212, 0, v212
	v_add_f32_e32 v212, 0x3727c5ac, v212
	v_rsq_f32_e32 v212, v212
	v_fma_f32 v36, -v88, v210, v36
	v_fma_f32 v37, -v89, v210, v37
	v_fma_f32 v38, -v90, v210, v38
	v_fma_f32 v39, -v91, v210, v39
	v_fma_f32 v36, v36, v212, v96
	v_fma_f32 v37, v37, v212, v97
	v_fma_f32 v38, v38, v212, v98
	v_fma_f32 v39, v39, v212, v99
	v_mul_f32_e32 v36, 0xbfb8aa3b, v36
	v_mul_f32_e32 v37, 0xbfb8aa3b, v37
	v_mul_f32_e32 v38, 0xbfb8aa3b, v38
	v_mul_f32_e32 v39, 0xbfb8aa3b, v39
	v_exp_f32_e32 v36, v36
	v_exp_f32_e32 v37, v37
	v_exp_f32_e32 v38, v38
	v_exp_f32_e32 v39, v39
	v_add_f32_e32 v36, 1.0, v36
	v_add_f32_e32 v37, 1.0, v37
	v_add_f32_e32 v38, 1.0, v38
	v_add_f32_e32 v39, 1.0, v39
	v_rcp_f32_e32 v36, v36
	v_rcp_f32_e32 v37, v37
	v_rcp_f32_e32 v38, v38
	v_rcp_f32_e32 v39, v39
	v_lshlrev_b32_e32 v202, 16, v188
	v_and_b32_e32 v203, 0xffff0000, v188
	v_lshlrev_b32_e32 v200, 16, v192
	v_and_b32_e32 v201, 0xffff0000, v192
	v_pk_add_f32 v[202:203], v[202:203], v[210:211] op_sel_hi:[1,0] neg_lo:[0,1] neg_hi:[0,1]
	v_pk_mul_f32 v[202:203], v[212:213], v[202:203] op_sel_hi:[0,1]
	v_pk_fma_f32 v[202:203], v[104:105], v[202:203], v[116:117]
	v_pk_fma_f32 v[36:37], v[36:37], v[200:201], v[202:203]
	v_lshlrev_b32_e32 v202, 16, v189
	v_and_b32_e32 v203, 0xffff0000, v189
	v_lshlrev_b32_e32 v200, 16, v193
	v_and_b32_e32 v201, 0xffff0000, v193
	v_pk_add_f32 v[202:203], v[202:203], v[210:211] op_sel_hi:[1,0] neg_lo:[0,1] neg_hi:[0,1]
	v_pk_mul_f32 v[202:203], v[212:213], v[202:203] op_sel_hi:[0,1]
	v_pk_fma_f32 v[202:203], v[106:107], v[202:203], v[118:119]
	v_pk_fma_f32 v[38:39], v[38:39], v[200:201], v[202:203]
	global_store_dwordx4 v224, v[36:39], s[8:9]
	v_cvt_pk_bf16_f32 v196, v36, v37
	v_cvt_pk_bf16_f32 v197, v38, v39
	v_fma_f32 v32, -v92, v210, v32
	v_fma_f32 v33, -v93, v210, v33
	v_fma_f32 v34, -v94, v210, v34
	v_fma_f32 v35, -v95, v210, v35
	v_fma_f32 v32, v32, v212, v100
	v_fma_f32 v33, v33, v212, v101
	v_fma_f32 v34, v34, v212, v102
	v_fma_f32 v35, v35, v212, v103
	v_mul_f32_e32 v32, 0xbfb8aa3b, v32
	v_mul_f32_e32 v33, 0xbfb8aa3b, v33
	v_mul_f32_e32 v34, 0xbfb8aa3b, v34
	v_mul_f32_e32 v35, 0xbfb8aa3b, v35
	v_exp_f32_e32 v32, v32
	v_exp_f32_e32 v33, v33
	v_exp_f32_e32 v34, v34
	v_exp_f32_e32 v35, v35
	v_add_f32_e32 v32, 1.0, v32
	v_add_f32_e32 v33, 1.0, v33
	v_add_f32_e32 v34, 1.0, v34
	v_add_f32_e32 v35, 1.0, v35
	v_rcp_f32_e32 v32, v32
	v_rcp_f32_e32 v33, v33
	v_rcp_f32_e32 v34, v34
	v_rcp_f32_e32 v35, v35
	v_lshlrev_b32_e32 v202, 16, v190
	v_and_b32_e32 v203, 0xffff0000, v190
	v_lshlrev_b32_e32 v200, 16, v194
	v_and_b32_e32 v201, 0xffff0000, v194
	v_pk_add_f32 v[202:203], v[202:203], v[210:211] op_sel_hi:[1,0] neg_lo:[0,1] neg_hi:[0,1]
	v_pk_mul_f32 v[202:203], v[212:213], v[202:203] op_sel_hi:[0,1]
	v_pk_fma_f32 v[202:203], v[108:109], v[202:203], v[124:125]
	v_pk_fma_f32 v[32:33], v[32:33], v[200:201], v[202:203]
	v_lshlrev_b32_e32 v202, 16, v191
	v_and_b32_e32 v203, 0xffff0000, v191
	v_lshlrev_b32_e32 v200, 16, v195
	v_and_b32_e32 v201, 0xffff0000, v195
	v_pk_add_f32 v[202:203], v[202:203], v[210:211] op_sel_hi:[1,0] neg_lo:[0,1] neg_hi:[0,1]
	v_pk_mul_f32 v[202:203], v[212:213], v[202:203] op_sel_hi:[0,1]
	v_pk_fma_f32 v[202:203], v[110:111], v[202:203], v[126:127]
	v_pk_fma_f32 v[34:35], v[34:35], v[200:201], v[202:203]
	global_store_dwordx4 v224, v[32:35], s[8:9] offset:16
	v_cvt_pk_bf16_f32 v198, v32, v33
	v_cvt_pk_bf16_f32 v199, v34, v35
	s_and_b64 vcc, exec, s[2:3]
	s_cbranch_vccz .Lpg_nx_11
	global_store_dwordx4 v226, v[196:199], s[90:91]

; __device__ __forceinline__ unsigned cvt_pk_bf16(float lo, float hi) { unsigned r; asm volatile("v_cvt_pk_bf16_f32 %0, %1, %2" : "=v"(r) : "v"(lo), "v"(hi)); return r; }
; __device__ __forceinline__ float bf_lo(unsigned w) { return __uint_as_float(w << 16); }
; __device__ __forceinline__ float bf_hi(unsigned w) { return __uint_as_float(w & 0xffff0000u); }
;     __device__ __forceinline__ void operator()(const f32x4 (&acc)[2][2][4][2], const Unit& u, int wr, int wc, int fr, int fq) const {
;     ...
;                 for (int m = 0; m < 4; ++m) { const int row = row0 + ai * HALF + m * 16; const size_t o2 = (size_t)row * ldc + col;
;                     const float s1 = ST[2 * row], s2 = ST[2 * row + 1], mu = s1 * (1.f / 2048.f), rstd = __builtin_amdgcn_rsqf(fmaxf(s2 * (1.f / 2048.f) - mu * mu, 0.f) + 1e-5f);
;                     const u32x4 zw = *(const u32x4*)(Zb + o2), pw = *(const u32x4*)(PE + o2); u32x4 xw;
; #pragma unroll
;                     for (int n = 0; n < 2; ++n) { const unsigned za = n ? zw.z : zw.x, zb2 = n ? zw.w : zw.y, pa = n ? pw.z : pw.x, pb = n ? pw.w : pw.y;
;                         const float zv[4] = {bf_lo(za), bf_hi(za), bf_lo(zb2), bf_hi(zb2)}, pv[4] = {bf_lo(pa), bf_hi(pa), bf_lo(pb), bf_hi(pb)}; const f32x4 a = acc[ai][bj][m][n]; f32x4 o;
; #pragma unroll
;                         for (int e = 0; e < 4; ++e) { const float sv = rstd * (a[e] - mu * c1[n][e]) + c2[n][e]; const float xl = (zv[e] - mu) * rstd * lg[n][e] + lb[n][e]; o[e] = xl + pv[e] * __builtin_amdgcn_rcpf(1.f + __expf(-sv)); }
;                         *(f32x4*)(OUTF + o2 + 4 * n) = o; if (n == 0) { xw.x = cvt_pk_bf16(o[0], o[1]); xw.y = cvt_pk_bf16(o[2], o[3]); } else { xw.z = cvt_pk_bf16(o[0], o[1]); xw.w = cvt_pk_bf16(o[2], o[3]); } }
;                     if (XB) *(u32x4*)(XB + o2) = xw; }
.Lpg_wd_12:
	v_pk_mul_f32 v[210:211], v[160:161], s[0:1] op_sel_hi:[1,0]
	v_lshlrev_b32_e32 v224, 1, v226
	v_fma_f32 v212, -v210, v210, v211
	v_max_f32_e32 v212, 0, v212
	v_add_f32_e32 v212, 0x3727c5ac, v212
	v_rsq_f32_e32 v212, v212
	v_fma_f32 v28, -v88, v210, v28
	v_fma_f32 v29, -v89, v210, v29
	v_fma_f32 v30, -v90, v210, v30
	v_fma_f32 v31, -v91, v210, v31
	v_fma_f32 v28, v28, v212, v96
	v_fma_f32 v29, v29, v212, v97
	v_fma_f32 v30, v30, v212, v98
	v_fma_f32 v31, v31, v212, v99
	v_mul_f32_e32 v28, 0xbfb8aa3b, v28
	v_mul_f32_e32 v29, 0xbfb8aa3b, v29
	v_mul_f32_e32 v30, 0xbfb8aa3b, v30
	v_mul_f32_e32 v31, 0xbfb8aa3b, v31
	v_exp_f32_e32 v28, v28
	v_exp_f32_e32 v29, v29
	v_exp_f32_e32 v30, v30
	v_exp_f32_e32 v31, v31
	v_add_f32_e32 v28, 1.0, v28
	v_add_f32_e32 v29, 1.0, v29
	v_add_f32_e32 v30, 1.0, v30
	v_add_f32_e32 v31, 1.0, v31
	v_rcp_f32_e32 v28, v28
	v_rcp_f32_e32 v29, v29
	v_rcp_f32_e32 v30, v30
	v_rcp_f32_e32 v31, v31
	v_lshlrev_b32_e32 v202, 16, v164
	v_and_b32_e32 v203, 0xffff0000, v164
	v_lshlrev_b32_e32 v200, 16, v184
	v_and_b32_e32 v201, 0xffff0000, v184
	v_pk_add_f32 v[202:203], v[202:203], v[210:211] op_sel_hi:[1,0] neg_lo:[0,1] neg_hi:[0,1]
	v_pk_mul_f32 v[202:203], v[212:213], v[202:203] op_sel_hi:[0,1]
	v_pk_fma_f32 v[202:203], v[104:105], v[202:203], v[116:117]
	v_pk_fma_f32 v[28:29], v[28:29], v[200:201], v[202:203]
	v_lshlrev_b32_e32 v202, 16, v165
	v_and_b32_e32 v203, 0xffff0000, v165
	v_lshlrev_b32_e32 v200, 16, v185
	v_and_b32_e32 v201, 0xffff0000, v185
	v_pk_add_f32 v[202:203], v[202:203], v[210:211] op_sel_hi:[1,0] neg_lo:[0,1] neg_hi:[0,1]
	v_pk_mul_f32 v[202:203], v[212:213], v[202:203] op_sel_hi:[0,1]
	v_pk_fma_f32 v[202:203], v[106:107], v[202:203], v[118:119]
	v_pk_fma_f32 v[30:31], v[30:31], v[200:201], v[202:203]
	global_store_dwordx4 v224, v[28:31], s[8:9]
	v_cvt_pk_bf16_f32 v196, v28, v29
	v_cvt_pk_bf16_f32 v197, v30, v31
	v_fma_f32 v24, -v92, v210, v24
	v_fma_f32 v25, -v93, v210, v25
	v_fma_f32 v26, -v94, v210, v26
	v_fma_f32 v27, -v95, v210, v27
	v_fma_f32 v24, v24, v212, v100
	v_fma_f32 v25, v25, v212, v101
	v_fma_f32 v26, v26, v212, v102
	v_fma_f32 v27, v27, v212, v103
	v_mul_f32_e32 v24, 0xbfb8aa3b, v24
	v_mul_f32_e32 v25, 0xbfb8aa3b, v25
	v_mul_f32_e32 v26, 0xbfb8aa3b, v26
	v_mul_f32_e32 v27, 0xbfb8aa3b, v27
	v_exp_f32_e32 v24, v24
	v_exp_f32_e32 v25, v25
	v_exp_f32_e32 v26, v26
	v_exp_f32_e32 v27, v27
	v_add_f32_e32 v24, 1.0, v24
	v_add_f32_e32 v25, 1.0, v25
	v_add_f32_e32 v26, 1.0, v26
	v_add_f32_e32 v27, 1.0, v27
	v_rcp_f32_e32 v24, v24
	v_rcp_f32_e32 v25, v25
	v_rcp_f32_e32 v26, v26
	v_rcp_f32_e32 v27, v27
	v_lshlrev_b32_e32 v202, 16, v166
	v_and_b32_e32 v203, 0xffff0000, v166
	v_lshlrev_b32_e32 v200, 16, v186
	v_and_b32_e32 v201, 0xffff0000, v186
	v_pk_add_f32 v[202:203], v[202:203], v[210:211] op_sel_hi:[1,0] neg_lo:[0,1] neg_hi:[0,1]
	v_pk_mul_f32 v[202:203], v[212:213], v[202:203] op_sel_hi:[0,1]
	v_pk_fma_f32 v[202:203], v[108:109], v[202:203], v[124:125]
	v_pk_fma_f32 v[24:25], v[24:25], v[200:201], v[202:203]
	v_lshlrev_b32_e32 v202, 16, v167
	v_and_b32_e32 v203, 0xffff0000, v167
	v_lshlrev_b32_e32 v200, 16, v187
	v_and_b32_e32 v201, 0xffff0000, v187
	v_pk_add_f32 v[202:203], v[202:203], v[210:211] op_sel_hi:[1,0] neg_lo:[0,1] neg_hi:[0,1]
	v_pk_mul_f32 v[202:203], v[212:213], v[202:203] op_sel_hi:[0,1]
	v_pk_fma_f32 v[202:203], v[110:111], v[202:203], v[126:127]
	v_pk_fma_f32 v[26:27], v[26:27], v[200:201], v[202:203]
	global_store_dwordx4 v224, v[24:27], s[8:9] offset:16
	v_cvt_pk_bf16_f32 v198, v24, v25
	v_cvt_pk_bf16_f32 v199, v26, v27
	s_and_b64 vcc, exec, s[2:3]
	s_cbranch_vccz .Lpg_nx_12
	global_store_dwordx4 v226, v[196:199], s[90:91]

; __device__ __forceinline__ unsigned cvt_pk_bf16(float lo, float hi) { unsigned r; asm volatile("v_cvt_pk_bf16_f32 %0, %1, %2" : "=v"(r) : "v"(lo), "v"(hi)); return r; }
; __device__ __forceinline__ float bf_lo(unsigned w) { return __uint_as_float(w << 16); }
; __device__ __forceinline__ float bf_hi(unsigned w) { return __uint_as_float(w & 0xffff0000u); }
;     __device__ __forceinline__ void operator()(const f32x4 (&acc)[2][2][4][2], const Unit& u, int wr, int wc, int fr, int fq) const {
;     ...
;                 for (int m = 0; m < 4; ++m) { const int row = row0 + ai * HALF + m * 16; const size_t o2 = (size_t)row * ldc + col;
;                     const float s1 = ST[2 * row], s2 = ST[2 * row + 1], mu = s1 * (1.f / 2048.f), rstd = __builtin_amdgcn_rsqf(fmaxf(s2 * (1.f / 2048.f) - mu * mu, 0.f) + 1e-5f);
;                     const u32x4 zw = *(const u32x4*)(Zb + o2), pw = *(const u32x4*)(PE + o2); u32x4 xw;
; #pragma unroll
;                     for (int n = 0; n < 2; ++n) { const unsigned za = n ? zw.z : zw.x, zb2 = n ? zw.w : zw.y, pa = n ? pw.z : pw.x, pb = n ? pw.w : pw.y;
;                         const float zv[4] = {bf_lo(za), bf_hi(za), bf_lo(zb2), bf_hi(zb2)}, pv[4] = {bf_lo(pa), bf_hi(pa), bf_lo(pb), bf_hi(pb)}; const f32x4 a = acc[ai][bj][m][n]; f32x4 o;
; #pragma unroll
;                         for (int e = 0; e < 4; ++e) { const float sv = rstd * (a[e] - mu * c1[n][e]) + c2[n][e]; const float xl = (zv[e] - mu) * rstd * lg[n][e] + lb[n][e]; o[e] = xl + pv[e] * __builtin_amdgcn_rcpf(1.f + __expf(-sv)); }
;                         *(f32x4*)(OUTF + o2 + 4 * n) = o; if (n == 0) { xw.x = cvt_pk_bf16(o[0], o[1]); xw.y = cvt_pk_bf16(o[2], o[3]); } else { xw.z = cvt_pk_bf16(o[0], o[1]); xw.w = cvt_pk_bf16(o[2], o[3]); } }
;                     if (XB) *(u32x4*)(XB + o2) = xw; }
.Lpg_wd_13:
	v_pk_mul_f32 v[210:211], v[162:163], s[0:1] op_sel_hi:[1,0]
	v_lshlrev_b32_e32 v224, 1, v226
	v_fma_f32 v212, -v210, v210, v211
	v_max_f32_e32 v212, 0, v212
	v_add_f32_e32 v212, 0x3727c5ac, v212
	v_rsq_f32_e32 v212, v212
	v_fma_f32 v20, -v88, v210, v20
	v_fma_f32 v21, -v89, v210, v21
	v_fma_f32 v22, -v90, v210, v22
	v_fma_f32 v23, -v91, v210, v23
	v_fma_f32 v20, v20, v212, v96
	v_fma_f32 v21, v21, v212, v97
	v_fma_f32 v22, v22, v212, v98
	v_fma_f32 v23, v23, v212, v99
	v_mul_f32_e32 v20, 0xbfb8aa3b, v20
	v_mul_f32_e32 v21, 0xbfb8aa3b, v21
	v_mul_f32_e32 v22, 0xbfb8aa3b, v22
	v_mul_f32_e32 v23, 0xbfb8aa3b, v23
	v_exp_f32_e32 v20, v20
	v_exp_f32_e32 v21, v21
	v_exp_f32_e32 v22, v22
	v_exp_f32_e32 v23, v23
	v_add_f32_e32 v20, 1.0, v20
	v_add_f32_e32 v21, 1.0, v21
	v_add_f32_e32 v22, 1.0, v22
	v_add_f32_e32 v23, 1.0, v23
	v_rcp_f32_e32 v20, v20
	v_rcp_f32_e32 v21, v21
	v_rcp_f32_e32 v22, v22
	v_rcp_f32_e32 v23, v23
	v_lshlrev_b32_e32 v202, 16, v188
	v_and_b32_e32 v203, 0xffff0000, v188
	v_lshlrev_b32_e32 v200, 16, v192
	v_and_b32_e32 v201, 0xffff0000, v192
	v_pk_add_f32 v[202:203], v[202:203], v[210:211] op_sel_hi:[1,0] neg_lo:[0,1] neg_hi:[0,1]
	v_pk_mul_f32 v[202:203], v[212:213], v[202:203] op_sel_hi:[0,1]
	v_pk_fma_f32 v[202:203], v[104:105], v[202:203], v[116:117]
	v_pk_fma_f32 v[20:21], v[20:21], v[200:201], v[202:203]
	v_lshlrev_b32_e32 v202, 16, v189
	v_and_b32_e32 v203, 0xffff0000, v189
	v_lshlrev_b32_e32 v200, 16, v193
	v_and_b32_e32 v201, 0xffff0000, v193
	v_pk_add_f32 v[202:203], v[202:203], v[210:211] op_sel_hi:[1,0] neg_lo:[0,1] neg_hi:[0,1]
	v_pk_mul_f32 v[202:203], v[212:213], v[202:203] op_sel_hi:[0,1]
	v_pk_fma_f32 v[202:203], v[106:107], v[202:203], v[118:119]
	v_pk_fma_f32 v[22:23], v[22:23], v[200:201], v[202:203]
	global_store_dwordx4 v224, v[20:23], s[8:9]
	v_cvt_pk_bf16_f32 v196, v20, v21
	v_cvt_pk_bf16_f32 v197, v22, v23
	v_fma_f32 v16, -v92, v210, v16
	v_fma_f32 v17, -v93, v210, v17
	v_fma_f32 v18, -v94, v210, v18
	v_fma_f32 v19, -v95, v210, v19
	v_fma_f32 v16, v16, v212, v100
	v_fma_f32 v17, v17, v212, v101
	v_fma_f32 v18, v18, v212, v102
	v_fma_f32 v19, v19, v212, v103
	v_mul_f32_e32 v16, 0xbfb8aa3b, v16
	v_mul_f32_e32 v17, 0xbfb8aa3b, v17
	v_mul_f32_e32 v18, 0xbfb8aa3b, v18
	v_mul_f32_e32 v19, 0xbfb8aa3b, v19
	v_exp_f32_e32 v16, v16
	v_exp_f32_e32 v17, v17
	v_exp_f32_e32 v18, v18
	v_exp_f32_e32 v19, v19
	v_add_f32_e32 v16, 1.0, v16
	v_add_f32_e32 v17, 1.0, v17
	v_add_f32_e32 v18, 1.0, v18
	v_add_f32_e32 v19, 1.0, v19
	v_rcp_f32_e32 v16, v16
	v_rcp_f32_e32 v17, v17
	v_rcp_f32_e32 v18, v18
	v_rcp_f32_e32 v19, v19
	v_lshlrev_b32_e32 v202, 16, v190
	v_and_b32_e32 v203, 0xffff0000, v190
	v_lshlrev_b32_e32 v200, 16, v194
	v_and_b32_e32 v201, 0xffff0000, v194
	v_pk_add_f32 v[202:203], v[202:203], v[210:211] op_sel_hi:[1,0] neg_lo:[0,1] neg_hi:[0,1]
	v_pk_mul_f32 v[202:203], v[212:213], v[202:203] op_sel_hi:[0,1]
	v_pk_fma_f32 v[202:203], v[108:109], v[202:203], v[124:125]
	v_pk_fma_f32 v[16:17], v[16:17], v[200:201], v[202:203]
	v_lshlrev_b32_e32 v202, 16, v191
	v_and_b32_e32 v203, 0xffff0000, v191
	v_lshlrev_b32_e32 v200, 16, v195
	v_and_b32_e32 v201, 0xffff0000, v195
	v_pk_add_f32 v[202:203], v[202:203], v[210:211] op_sel_hi:[1,0] neg_lo:[0,1] neg_hi:[0,1]
	v_pk_mul_f32 v[202:203], v[212:213], v[202:203] op_sel_hi:[0,1]
	v_pk_fma_f32 v[202:203], v[110:111], v[202:203], v[126:127]
	v_pk_fma_f32 v[18:19], v[18:19], v[200:201], v[202:203]
	global_store_dwordx4 v224, v[16:19], s[8:9] offset:16
	v_cvt_pk_bf16_f32 v198, v16, v17
	v_cvt_pk_bf16_f32 v199, v18, v19
	s_and_b64 vcc, exec, s[2:3]
	s_cbranch_vccz .Lpg_nx_13
	global_store_dwordx4 v226, v[196:199], s[90:91]

; __device__ __forceinline__ unsigned cvt_pk_bf16(float lo, float hi) { unsigned r; asm volatile("v_cvt_pk_bf16_f32 %0, %1, %2" : "=v"(r) : "v"(lo), "v"(hi)); return r; }
; __device__ __forceinline__ float bf_lo(unsigned w) { return __uint_as_float(w << 16); }
; __device__ __forceinline__ float bf_hi(unsigned w) { return __uint_as_float(w & 0xffff0000u); }
;     __device__ __forceinline__ void operator()(const f32x4 (&acc)[2][2][4][2], const Unit& u, int wr, int wc, int fr, int fq) const {
;     ...
;                 for (int m = 0; m < 4; ++m) { const int row = row0 + ai * HALF + m * 16; const size_t o2 = (size_t)row * ldc + col;
;                     const float s1 = ST[2 * row], s2 = ST[2 * row + 1], mu = s1 * (1.f / 2048.f), rstd = __builtin_amdgcn_rsqf(fmaxf(s2 * (1.f / 2048.f) - mu * mu, 0.f) + 1e-5f);
;                     const u32x4 zw = *(const u32x4*)(Zb + o2), pw = *(const u32x4*)(PE + o2); u32x4 xw;
; #pragma unroll
;                     for (int n = 0; n < 2; ++n) { const unsigned za = n ? zw.z : zw.x, zb2 = n ? zw.w : zw.y, pa = n ? pw.z : pw.x, pb = n ? pw.w : pw.y;
;                         const float zv[4] = {bf_lo(za), bf_hi(za), bf_lo(zb2), bf_hi(zb2)}, pv[4] = {bf_lo(pa), bf_hi(pa), bf_lo(pb), bf_hi(pb)}; const f32x4 a = acc[ai][bj][m][n]; f32x4 o;
; #pragma unroll
;                         for (int e = 0; e < 4; ++e) { const float sv = rstd * (a[e] - mu * c1[n][e]) + c2[n][e]; const float xl = (zv[e] - mu) * rstd * lg[n][e] + lb[n][e]; o[e] = xl + pv[e] * __builtin_amdgcn_rcpf(1.f + __expf(-sv)); }
;                         *(f32x4*)(OUTF + o2 + 4 * n) = o; if (n == 0) { xw.x = cvt_pk_bf16(o[0], o[1]); xw.y = cvt_pk_bf16(o[2], o[3]); } else { xw.z = cvt_pk_bf16(o[0], o[1]); xw.w = cvt_pk_bf16(o[2], o[3]); } }
;                     if (XB) *(u32x4*)(XB + o2) = xw; }
.Lpg_wd_14:
	v_pk_mul_f32 v[210:211], v[160:161], s[0:1] op_sel_hi:[1,0]
	v_lshlrev_b32_e32 v224, 1, v226
	v_fma_f32 v212, -v210, v210, v211
	v_max_f32_e32 v212, 0, v212
	v_add_f32_e32 v212, 0x3727c5ac, v212
	v_rsq_f32_e32 v212, v212
	v_fma_f32 v12, -v88, v210, v12
	v_fma_f32 v13, -v89, v210, v13
	v_fma_f32 v14, -v90, v210, v14
	v_fma_f32 v15, -v91, v210, v15
	v_fma_f32 v12, v12, v212, v96
	v_fma_f32 v13, v13, v212, v97
	v_fma_f32 v14, v14, v212, v98
	v_fma_f32 v15, v15, v212, v99
	v_mul_f32_e32 v12, 0xbfb8aa3b, v12
	v_mul_f32_e32 v13, 0xbfb8aa3b, v13
	v_mul_f32_e32 v14, 0xbfb8aa3b, v14
	v_mul_f32_e32 v15, 0xbfb8aa3b, v15
	v_exp_f32_e32 v12, v12
	v_exp_f32_e32 v13, v13
	v_exp_f32_e32 v14, v14
	v_exp_f32_e32 v15, v15
	v_add_f32_e32 v12, 1.0, v12
	v_add_f32_e32 v13, 1.0, v13
	v_add_f32_e32 v14, 1.0, v14
	v_add_f32_e32 v15, 1.0, v15
	v_rcp_f32_e32 v12, v12
	v_rcp_f32_e32 v13, v13
	v_rcp_f32_e32 v14, v14
	v_rcp_f32_e32 v15, v15
	v_lshlrev_b32_e32 v202, 16, v164
	v_and_b32_e32 v203, 0xffff0000, v164
	v_lshlrev_b32_e32 v200, 16, v184
	v_and_b32_e32 v201, 0xffff0000, v184
	v_pk_add_f32 v[202:203], v[202:203], v[210:211] op_sel_hi:[1,0] neg_lo:[0,1] neg_hi:[0,1]
	v_pk_mul_f32 v[202:203], v[212:213], v[202:203] op_sel_hi:[0,1]
	v_pk_fma_f32 v[202:203], v[104:105], v[202:203], v[116:117]
	v_pk_fma_f32 v[12:13], v[12:13], v[200:201], v[202:203]
	v_lshlrev_b32_e32 v202, 16, v165
	v_and_b32_e32 v203, 0xffff0000, v165
	v_lshlrev_b32_e32 v200, 16, v185
	v_and_b32_e32 v201, 0xffff0000, v185
	v_pk_add_f32 v[202:203], v[202:203], v[210:211] op_sel_hi:[1,0] neg_lo:[0,1] neg_hi:[0,1]
	v_pk_mul_f32 v[202:203], v[212:213], v[202:203] op_sel_hi:[0,1]
	v_pk_fma_f32 v[202:203], v[106:107], v[202:203], v[118:119]
	v_pk_fma_f32 v[14:15], v[14:15], v[200:201], v[202:203]
	global_store_dwordx4 v224, v[12:15], s[8:9]
	v_cvt_pk_bf16_f32 v196, v12, v13
	v_cvt_pk_bf16_f32 v197, v14, v15
	v_fma_f32 v8, -v92, v210, v8
	v_fma_f32 v9, -v93, v210, v9
	v_fma_f32 v10, -v94, v210, v10
	v_fma_f32 v11, -v95, v210, v11
	v_fma_f32 v8, v8, v212, v100
	v_fma_f32 v9, v9, v212, v101
	v_fma_f32 v10, v10, v212, v102
	v_fma_f32 v11, v11, v212, v103
	v_mul_f32_e32 v8, 0xbfb8aa3b, v8
	v_mul_f32_e32 v9, 0xbfb8aa3b, v9
	v_mul_f32_e32 v10, 0xbfb8aa3b, v10
	v_mul_f32_e32 v11, 0xbfb8aa3b, v11
	v_exp_f32_e32 v8, v8
	v_exp_f32_e32 v9, v9
	v_exp_f32_e32 v10, v10
	v_exp_f32_e32 v11, v11
	v_add_f32_e32 v8, 1.0, v8
	v_add_f32_e32 v9, 1.0, v9
	v_add_f32_e32 v10, 1.0, v10
	v_add_f32_e32 v11, 1.0, v11
	v_rcp_f32_e32 v8, v8
	v_rcp_f32_e32 v9, v9
	v_rcp_f32_e32 v10, v10
	v_rcp_f32_e32 v11, v11
	v_lshlrev_b32_e32 v202, 16, v166
	v_and_b32_e32 v203, 0xffff0000, v166
	v_lshlrev_b32_e32 v200, 16, v186
	v_and_b32_e32 v201, 0xffff0000, v186
	v_pk_add_f32 v[202:203], v[202:203], v[210:211] op_sel_hi:[1,0] neg_lo:[0,1] neg_hi:[0,1]
	v_pk_mul_f32 v[202:203], v[212:213], v[202:203] op_sel_hi:[0,1]
	v_pk_fma_f32 v[202:203], v[108:109], v[202:203], v[124:125]
	v_pk_fma_f32 v[8:9], v[8:9], v[200:201], v[202:203]
	v_lshlrev_b32_e32 v202, 16, v167
	v_and_b32_e32 v203, 0xffff0000, v167
	v_lshlrev_b32_e32 v200, 16, v187
	v_and_b32_e32 v201, 0xffff0000, v187
	v_pk_add_f32 v[202:203], v[202:203], v[210:211] op_sel_hi:[1,0] neg_lo:[0,1] neg_hi:[0,1]
	v_pk_mul_f32 v[202:203], v[212:213], v[202:203] op_sel_hi:[0,1]
	v_pk_fma_f32 v[202:203], v[110:111], v[202:203], v[126:127]
	v_pk_fma_f32 v[10:11], v[10:11], v[200:201], v[202:203]
	global_store_dwordx4 v224, v[8:11], s[8:9] offset:16
	v_cvt_pk_bf16_f32 v198, v8, v9
	v_cvt_pk_bf16_f32 v199, v10, v11
	s_and_b64 vcc, exec, s[2:3]
	s_cbranch_vccz .Lpg_nx_14
	global_store_dwordx4 v226, v[196:199], s[90:91]
.Lpg_nx_14:
	v_mov_b32_e32 v226, v204
	s_and_b64 vcc, exec, s[2:3]
	s_cbranch_vccz .Lpg_w2_15
	s_waitcnt vmcnt(3)
	s_branch .Lpg_wd_15
; __device__ __forceinline__ float bf_lo(unsigned w) { return __uint_as_float(w << 16); }
; #define PG8_BAR __builtin_amdgcn_s_barrier()
;     __device__ __forceinline__ void operator()(const f32x4 (&acc)[2][2][4][2], const Unit& u, int wr, int wc, int fr, int fq) const {
;     ...
;                 for (int m = 0; m < 4; ++m) { const int row = row0 + ai * HALF + m * 16; const size_t o2 = (size_t)row * ldc + col;
;                     const float s1 = ST[2 * row], s2 = ST[2 * row + 1], mu = s1 * (1.f / 2048.f), rstd = __builtin_amdgcn_rsqf(fmaxf(s2 * (1.f / 2048.f) - mu * mu, 0.f) + 1e-5f);
;                     const u32x4 zw = *(const u32x4*)(Zb + o2), pw = *(const u32x4*)(PE + o2); u32x4 xw;
; #pragma unroll
;                     for (int n = 0; n < 2; ++n) { const unsigned za = n ? zw.z : zw.x, zb2 = n ? zw.w : zw.y, pa = n ? pw.z : pw.x, pb = n ? pw.w : pw.y;
;                         const float zv[4] = {bf_lo(za), bf_hi(za), bf_lo(zb2), bf_hi(zb2)}, pv[4] = {bf_lo(pa), bf_hi(pa), bf_lo(pb), bf_hi(pb)}; const f32x4 a = acc[ai][bj][m][n]; f32x4 o;
; #pragma unroll
;                         for (int e = 0; e < 4; ++e) { const float sv = rstd * (a[e] - mu * c1[n][e]) + c2[n][e]; const float xl = (zv[e] - mu) * rstd * lg[n][e] + lb[n][e]; o[e] = xl + pv[e] * __builtin_amdgcn_rcpf(1.f + __expf(-sv)); }
;                         *(f32x4*)(OUTF + o2 + 4 * n) = o; if (n == 0) { xw.x = cvt_pk_bf16(o[0], o[1]); xw.y = cvt_pk_bf16(o[2], o[3]); } else { xw.z = cvt_pk_bf16(o[0], o[1]); xw.w = cvt_pk_bf16(o[2], o[3]); } }
;                     if (XB) *(u32x4*)(XB + o2) = xw; }
; template <class Epi, class Sched, bool ALIGN_EPI = false, bool SP2 = false>
; __device__ __forceinline__ void gemm_phase(PG8_LAS unsigned char* lds, const Gemm g, const Sched& S, const Epi& E) {
;     ...
;         if constexpr (ALIGN_EPI) { if (wr == 0) PG8_BAR; }
;         if constexpr (!Epi::AFTER_DRAIN) { E(acc, cur, wr, wc, fr, fq); S.done(cur); }
;         if (!has_next) break;
; #pragma unroll
;         for (int a = 0; a < 2; ++a)
; #pragma unroll
;             for (int b = 0; b < 2; ++b)
; #pragma unroll
;                 for (int m = 0; m < 4; ++m)
; #pragma unroll
;                     for (int n = 0; n < 2; ++n) acc[a][b][m][n] = (f32x4){0.f, 0.f, 0.f, 0.f};
;         cur = nxt; cA = nA; cB = nB; ++ui;
;         if constexpr (ALIGN_EPI) { if (wr == 1) PG8_BAR; }
;     }
.Lpg_w2_15:
	s_waitcnt vmcnt(2)
.Lpg_wd_15:
	v_pk_mul_f32 v[210:211], v[162:163], s[0:1] op_sel_hi:[1,0]
	v_lshlrev_b32_e32 v224, 1, v226
	v_fma_f32 v212, -v210, v210, v211
	v_max_f32_e32 v212, 0, v212
	v_add_f32_e32 v212, 0x3727c5ac, v212
	v_rsq_f32_e32 v212, v212
	v_fma_f32 v4, -v88, v210, v4
	v_fma_f32 v5, -v89, v210, v5
	v_fma_f32 v6, -v90, v210, v6
	v_fma_f32 v7, -v91, v210, v7
	v_fma_f32 v4, v4, v212, v96
	v_fma_f32 v5, v5, v212, v97
	v_fma_f32 v6, v6, v212, v98
	v_fma_f32 v7, v7, v212, v99
	v_mul_f32_e32 v4, 0xbfb8aa3b, v4
	v_mul_f32_e32 v5, 0xbfb8aa3b, v5
	v_mul_f32_e32 v6, 0xbfb8aa3b, v6
	v_mul_f32_e32 v7, 0xbfb8aa3b, v7
	v_exp_f32_e32 v4, v4
	v_exp_f32_e32 v5, v5
	v_exp_f32_e32 v6, v6
	v_exp_f32_e32 v7, v7
	v_add_f32_e32 v4, 1.0, v4
	v_add_f32_e32 v5, 1.0, v5
	v_add_f32_e32 v6, 1.0, v6
	v_add_f32_e32 v7, 1.0, v7
	v_rcp_f32_e32 v4, v4
	v_rcp_f32_e32 v5, v5
	v_rcp_f32_e32 v6, v6
	v_rcp_f32_e32 v7, v7
	v_lshlrev_b32_e32 v202, 16, v188
	v_and_b32_e32 v203, 0xffff0000, v188
	v_lshlrev_b32_e32 v200, 16, v192
	v_and_b32_e32 v201, 0xffff0000, v192
	v_pk_add_f32 v[202:203], v[202:203], v[210:211] op_sel_hi:[1,0] neg_lo:[0,1] neg_hi:[0,1]
	v_pk_mul_f32 v[202:203], v[212:213], v[202:203] op_sel_hi:[0,1]
	v_pk_fma_f32 v[202:203], v[104:105], v[202:203], v[116:117]
	v_pk_fma_f32 v[4:5], v[4:5], v[200:201], v[202:203]
	v_lshlrev_b32_e32 v202, 16, v189
	v_and_b32_e32 v203, 0xffff0000, v189
	v_lshlrev_b32_e32 v200, 16, v193
	v_and_b32_e32 v201, 0xffff0000, v193
	v_pk_add_f32 v[202:203], v[202:203], v[210:211] op_sel_hi:[1,0] neg_lo:[0,1] neg_hi:[0,1]
	v_pk_mul_f32 v[202:203], v[212:213], v[202:203] op_sel_hi:[0,1]
	v_pk_fma_f32 v[202:203], v[106:107], v[202:203], v[118:119]
	v_pk_fma_f32 v[6:7], v[6:7], v[200:201], v[202:203]
	global_store_dwordx4 v224, v[4:7], s[8:9]
	v_cvt_pk_bf16_f32 v196, v4, v5
	v_cvt_pk_bf16_f32 v197, v6, v7
	v_fma_f32 v0, -v92, v210, v0
	v_fma_f32 v1, -v93, v210, v1
	v_fma_f32 v2, -v94, v210, v2
	v_fma_f32 v3, -v95, v210, v3
	v_fma_f32 v0, v0, v212, v100
	v_fma_f32 v1, v1, v212, v101
	v_fma_f32 v2, v2, v212, v102
	v_fma_f32 v3, v3, v212, v103
	v_mul_f32_e32 v0, 0xbfb8aa3b, v0
	v_mul_f32_e32 v1, 0xbfb8aa3b, v1
	v_mul_f32_e32 v2, 0xbfb8aa3b, v2
	v_mul_f32_e32 v3, 0xbfb8aa3b, v3
	v_exp_f32_e32 v0, v0
	v_exp_f32_e32 v1, v1
	v_exp_f32_e32 v2, v2
	v_exp_f32_e32 v3, v3
	v_add_f32_e32 v0, 1.0, v0
	v_add_f32_e32 v1, 1.0, v1
	v_add_f32_e32 v2, 1.0, v2
	v_add_f32_e32 v3, 1.0, v3
	v_rcp_f32_e32 v0, v0
	v_rcp_f32_e32 v1, v1
	v_rcp_f32_e32 v2, v2
	v_rcp_f32_e32 v3, v3
	v_lshlrev_b32_e32 v202, 16, v190
	v_and_b32_e32 v203, 0xffff0000, v190
	v_lshlrev_b32_e32 v200, 16, v194
	v_and_b32_e32 v201, 0xffff0000, v194
	v_pk_add_f32 v[202:203], v[202:203], v[210:211] op_sel_hi:[1,0] neg_lo:[0,1] neg_hi:[0,1]
	v_pk_mul_f32 v[202:203], v[212:213], v[202:203] op_sel_hi:[0,1]
	v_pk_fma_f32 v[202:203], v[108:109], v[202:203], v[124:125]
	v_pk_fma_f32 v[0:1], v[0:1], v[200:201], v[202:203]
	v_lshlrev_b32_e32 v202, 16, v191
	v_and_b32_e32 v203, 0xffff0000, v191
	v_lshlrev_b32_e32 v200, 16, v195
	v_and_b32_e32 v201, 0xffff0000, v195
	v_pk_add_f32 v[202:203], v[202:203], v[210:211] op_sel_hi:[1,0] neg_lo:[0,1] neg_hi:[0,1]
	v_pk_mul_f32 v[202:203], v[212:213], v[202:203] op_sel_hi:[0,1]
	v_pk_fma_f32 v[202:203], v[110:111], v[202:203], v[126:127]
	v_pk_fma_f32 v[2:3], v[2:3], v[200:201], v[202:203]
	global_store_dwordx4 v224, v[0:3], s[8:9] offset:16
	v_cvt_pk_bf16_f32 v198, v0, v1
	v_cvt_pk_bf16_f32 v199, v2, v3
	s_and_b64 vcc, exec, s[2:3]
	s_cbranch_vccz .Lpg_nx_15
	global_store_dwordx4 v226, v[196:199], s[90:91]
.Lpg_nx_15:
.LBB0_1376:
	s_andn2_b64 vcc, exec, s[38:39]
	s_mov_b64 s[0:1], -1
	s_cbranch_vccnz .LBB0_1333
	s_andn2_b64 vcc, exec, s[88:89]
	s_cbranch_vccnz .LBB0_1332
	s_barrier
	s_branch .LBB0_1332
